# cross-attention K/V staging loop software-pipelined; MoBA item-loop byte shrinks; FFN-up silu constant in SGPR
# baseline (speedup 1.0000x reference)
; #define LAS __attribute__((address_space(3)))
; __device__ __forceinline__ void sub_load(Sub32& r, const bf16* kt, const bf16* vt, int lane) {
; #pragma unroll
;     for (int i = 0; i < 4; ++i) { r.k[i] = *(const u32x4*)(kt + (i * 64 + lane) * 8); r.v[i] = *(const u32x4*)(vt + (i * 64 + lane) * 8); }
; }
; __device__ __forceinline__ void sub_write(const Sub32& r, lbyte* kbuf, lbyte* vbuf, int lane) {
; #pragma unroll
;     for (int i = 0; i < 4; ++i) { const int ci = i * 64 + lane; *(LAS u32x4*)(kbuf + (ci >> 3) * KP64 + (ci & 7) * 16) = r.k[i]; *(LAS u32x4*)(vbuf + (ci >> 3) * MC_VPR + (ci & 7) * 16) = r.v[i]; }
; }
; template <bool CAUSAL> __device__ __forceinline__ void moba_span(lbyte* kbuf, lbyte* vbuf, const bf16* Kh, const bf16* Vh, int kpos0, int nsub, const s16x8* qf, int tq, bool valid, int qlo, int qhi, ...
;     Sub32 st; sub_load(st, Kh + (size_t)kpos0 * 64, Vh + (size_t)kpos0 * 64, lane);
; #pragma unroll 1
;     for (int su = 0; su < nsub; ++su) {
;         const int key0 = kpos0 + 32 * su;
;         sub_write(st, kbuf, vbuf, lane);
;         if (su + 1 < nsub) sub_load(st, Kh + (size_t)(key0 + 32) * 64, Vh + (size_t)(key0 + 32) * 64, lane);
.LBB0_665:
	s_cmpk_eq_i32 s11, 0xff20
	s_waitcnt vmcnt(0)
	ds_write_b128 v251, v[98:101] offset:36864
	ds_write_b128 v251, v[122:125] offset:41472
	ds_write_b128 v251, v[106:109] offset:38016
	ds_write_b128 v251, v[126:129] offset:42624
	ds_write_b128 v251, v[130:133] offset:39168
	ds_write_b128 v251, v[138:141] offset:43776
	ds_write_b128 v251, v[134:137] offset:40320
	ds_write_b128 v251, v[142:145] offset:44928
	s_cbranch_scc1 .LBB0_667
	s_ashr_i32 s23, s22, 31
	s_lshl_b64 s[24:25], s[22:23], 7
	v_lshl_add_u64 v[34:35], v[190:191], 0, s[24:25]
	v_lshl_add_u64 v[36:37], v[192:193], 0, s[24:25]
	global_load_dwordx4 v[98:101], v[34:35], off
	global_load_dwordx4 v[106:109], v[34:35], off offset:1024
	global_load_dwordx4 v[122:125], v[36:37], off
	global_load_dwordx4 v[126:129], v[36:37], off offset:1024
	global_load_dwordx4 v[130:133], v[34:35], off offset:2048
	global_load_dwordx4 v[134:137], v[34:35], off offset:3072
	global_load_dwordx4 v[138:141], v[36:37], off offset:2048
	global_load_dwordx4 v[142:145], v[36:37], off offset:3072
; #define LDS_FENCE() asm volatile("" ::: "memory")
; template <bool CAUSAL> __device__ __forceinline__ void moba_span(lbyte* kbuf, lbyte* vbuf, const bf16* Kh, const bf16* Vh, int kpos0, int nsub, const s16x8* qf, int tq, bool valid, int qlo, int qhi, ...
;     ...
;         load_k<4>(kf, kbuf, KP64, l31, h); load_v_tr<2>(vf, vbuf, lane); LDS_FENCE();
;         qk1<4>(s[0], kf, qf);
;         const int dmin = qlo - (key0 + 31), dmax = qhi - key0;
;         const int bmin = t5_bucket(dmin > 0 ? dmin : 0), bmax = t5_bucket(dmax > 0 ? dmax : 0);
;         if (!CAUSAL && bmax - bmin <= 1) {
;             const float t0 = tab[bmin], t1 = tab[bmax]; const int th1 = thr[bmax];
;             float mxr = s[0][0];
; #pragma unroll
;             for (int r = 1; r < 16; ++r) mxr = fmaxf(mxr, s[0][r]);
;             mxr = pair_max(mxr);
;             const float cL = valid ? 0.125f * LOG2E : 0.f, bL = valid ? t0 : -INFINITY, mx = valid ? mxr * (0.125f * LOG2E) + fmaxf(t0, t1) : -INFINITY;
;             const bool grow = mx > m + 8.0f; const float mn = grow ? mx : m, off = bL - mn, offB = off + (t1 - t0);
;             if (__any(grow)) { const float alpha = __builtin_amdgcn_exp2f(m - mn); l *= alpha; o[0] = o[0] * alpha; o[1] = o[1] * alpha; }
;             m = mn;
;             const int x1 = (bmax > bmin) ? tq - key0 - th1 : -0x40000000; f32x2_t sum2 = {0.f, 0.f};
; #pragma unroll
;             for (int r = 0; r < 16; r += 2) { const int kk = kkrow(r, h);
;                 const f32x2_t ob = {x1 >= kk ? offB : off, x1 >= kk + 1 ? offB : off}; f32x2_t v = {s[0][r], s[0][r + 1]}; v = v * (f32x2_t){cL, cL} + ob;
;                 const float e0 = __builtin_amdgcn_exp2f(v.x), e1 = __builtin_amdgcn_exp2f(v.y); s[0][r] = e0; s[0][r + 1] = e1; sum2 += (f32x2_t){e0, e1}; }
;             l += pair_sum(sum2.x + sum2.y);
;         } else {
;             float bb[16];
; #pragma unroll
;             for (int r = 0; r < 16; ++r) { int dist = tq - (key0 + kkrow(r, h)); dist = dist > 0 ? dist : 0; bb[r] = dtab[dist < MC_NDT - 1 ? dist : MC_NDT - 1]; }
;             LDS_FENCE();
; #pragma unroll
;             for (int r = 0; r < 16; ++r) { const int dist = tq - (key0 + kkrow(r, h)); const bool ok = valid && (!CAUSAL || dist >= 0); s[0][r] = ok ? s[0][r] * (0.125f * LOG2E) + bb[r] : -INFINITY; }
;             softmax_upd<1, 2>(s, m, l, o);
.LBB0_667:
	ds_read_b128 v[34:37], v252 offset:36864
	ds_read_b128 v[38:41], v252 offset:36896
	ds_read_b128 v[42:45], v252 offset:36928
	ds_read_b128 v[46:49], v252 offset:36960
	ds_read_b64_tr_b16 v[158:159], v253 offset:41472
	ds_read_b64_tr_b16 v[160:161], v253 offset:42048
	ds_read_b64_tr_b16 v[156:157], v253 offset:42112
	ds_read_b64_tr_b16 v[154:155], v253 offset:41536
	s_waitcnt lgkmcnt(7)
	v_mfma_f32_32x32x16_bf16 v[66:81], v[34:37], v[102:105], 0
	s_add_i32 s15, s14, s11
	s_sub_i32 s17, s15, 31
	s_max_i32 s23, s17, 16
	s_flbit_i32_b32 s24, s23
	s_lshl_b32 s24, s24, 1
	s_sub_i32 s26, 62, s24
	s_add_i32 s21, s15, 0xff
	s_max_i32 s15, s17, 0
	s_mul_i32 s23, s23, s23
	s_lshl_b32 s24, 2, s26
	s_waitcnt lgkmcnt(6)
	v_mfma_f32_32x32x16_bf16 v[66:81], v[38:41], v[110:113], v[66:81]
	s_cmp_ge_u32 s23, s24
	s_cselect_b32 s23, 1, 0
	ds_read_b64_tr_b16 v[150:151], v253 offset:43776
	ds_read_b64_tr_b16 v[152:153], v253 offset:44352
	ds_read_b64_tr_b16 v[148:149], v253 offset:44416
	ds_read_b64_tr_b16 v[146:147], v253 offset:43840
	s_or_b32 s23, s26, s23
	s_min_u32 s23, s23, 23
	s_add_i32 s23, s23, 8
	s_cmp_lt_i32 s17, 16
	s_waitcnt lgkmcnt(9)
	v_mfma_f32_32x32x16_bf16 v[66:81], v[42:45], v[114:117], v[66:81]
	s_cselect_b32 s15, s15, s23
	s_max_i32 s23, s21, 16
	s_flbit_i32_b32 s24, s23
	s_lshl_b32 s24, s24, 1
	s_sub_i32 s26, 62, s24
	s_max_i32 s17, s21, 0
	s_mul_i32 s23, s23, s23
	s_lshl_b32 s24, 2, s26
	s_cmp_ge_u32 s23, s24
	s_cselect_b32 s23, 1, 0
	s_waitcnt lgkmcnt(8)
	v_mfma_f32_32x32x16_bf16 v[66:81], v[46:49], v[118:121], v[66:81]
	s_or_b32 s23, s26, s23
	s_min_u32 s23, s23, 23
	s_add_i32 s23, s23, 8
	s_cmp_lt_i32 s21, 16
	s_cselect_b32 s17, s17, s23
	s_sub_i32 s21, s17, s15
	s_mov_b64 s[24:25], -1
	s_cmp_gt_i32 s21, 1
	v_add_f32_e32 v0, 0x41000000, v231
	s_cbranch_scc0 .LBB0_671
	v_add_u32_e32 v34, s11, v237
	v_med3_i32 v35, v34, 0, v239
	v_add_u32_e32 v36, -1, v34
	v_add_u32_e32 v37, -2, v34
	v_add_u32_e32 v38, -3, v34
	v_add_u32_e32 v39, -8, v34
	v_add_u32_e32 v40, -9, v34
	v_add_u32_e32 v41, -10, v34
	v_add_u32_e32 v42, -11, v34
	v_add_u32_e32 v43, -16, v34
	v_subrev_u32_e32 v44, 17, v34
	v_subrev_u32_e32 v45, 18, v34
	v_subrev_u32_e32 v46, 19, v34
	v_subrev_u32_e32 v47, 24, v34
	v_subrev_u32_e32 v48, 25, v34
	v_subrev_u32_e32 v49, 26, v34
	v_subrev_u32_e32 v34, 27, v34
	v_med3_i32 v36, v36, 0, v239
	v_med3_i32 v37, v37, 0, v239
	v_med3_i32 v38, v38, 0, v239
	v_med3_i32 v39, v39, 0, v239
	v_med3_i32 v40, v40, 0, v239
	v_med3_i32 v41, v41, 0, v239
	v_med3_i32 v42, v42, 0, v239
	v_med3_i32 v43, v43, 0, v239
	v_med3_i32 v44, v44, 0, v239
	v_med3_i32 v45, v45, 0, v239
	v_med3_i32 v46, v46, 0, v239
	v_med3_i32 v47, v47, 0, v239
	v_med3_i32 v48, v48, 0, v239
	v_med3_i32 v49, v49, 0, v239
	v_med3_i32 v34, v34, 0, v239
	v_lshl_add_u32 v35, v35, 2, s82
	v_lshl_add_u32 v36, v36, 2, s82
	v_lshl_add_u32 v37, v37, 2, s82
	v_lshl_add_u32 v38, v38, 2, s82
	v_lshl_add_u32 v39, v39, 2, s82
	v_lshl_add_u32 v40, v40, 2, s82
	v_lshl_add_u32 v41, v41, 2, s82
	v_lshl_add_u32 v42, v42, 2, s82
	v_lshl_add_u32 v43, v43, 2, s82
	v_lshl_add_u32 v44, v44, 2, s82
	v_lshl_add_u32 v45, v45, 2, s82
	v_lshl_add_u32 v46, v46, 2, s82
	v_lshl_add_u32 v47, v47, 2, s82
	v_lshl_add_u32 v48, v48, 2, s82
	v_lshl_add_u32 v49, v49, 2, s82
	v_lshl_add_u32 v34, v34, 2, s82
	ds_read_b32 v35, v35
	ds_read_b32 v36, v36
	ds_read_b32 v37, v37
	ds_read_b32 v38, v38
	ds_read_b32 v39, v39
	ds_read_b32 v40, v40
	ds_read_b32 v41, v41
	ds_read_b32 v42, v42
	ds_read_b32 v43, v43
	ds_read_b32 v44, v44
	ds_read_b32 v45, v45
	ds_read_b32 v46, v46
	ds_read_b32 v47, v47
	ds_read_b32 v48, v48
	ds_read_b32 v49, v49
	ds_read_b32 v34, v34
	s_waitcnt lgkmcnt(14)
	v_fmac_f32_e32 v35, 0x3e38aa3b, v66
	v_fmac_f32_e32 v36, 0x3e38aa3b, v67
	v_cndmask_b32_e64 v82, v238, v35, s[8:9]
	v_cndmask_b32_e64 v83, v238, v36, s[8:9]
	s_waitcnt lgkmcnt(13)
	v_fmac_f32_e32 v37, 0x3e38aa3b, v68
	s_waitcnt lgkmcnt(12)
	v_fmac_f32_e32 v38, 0x3e38aa3b, v69
	s_waitcnt lgkmcnt(0)
	v_fmac_f32_e32 v34, 0x3e38aa3b, v81
	v_cndmask_b32_e64 v84, v238, v37, s[8:9]
	v_cndmask_b32_e64 v85, v238, v38, s[8:9]
	v_fmac_f32_e32 v39, 0x3e38aa3b, v70
	v_fmac_f32_e32 v40, 0x3e38aa3b, v71
	v_cndmask_b32_e64 v97, v238, v34, s[8:9]
	v_max_f32_e32 v34, v82, v83
	v_cndmask_b32_e64 v86, v238, v39, s[8:9]
	v_cndmask_b32_e64 v87, v238, v40, s[8:9]
	v_fmac_f32_e32 v41, 0x3e38aa3b, v72
	v_fmac_f32_e32 v42, 0x3e38aa3b, v73
	v_max3_f32 v34, v34, v84, v85
	v_cndmask_b32_e64 v88, v238, v41, s[8:9]
	v_cndmask_b32_e64 v89, v238, v42, s[8:9]
	v_fmac_f32_e32 v43, 0x3e38aa3b, v74
	v_fmac_f32_e32 v44, 0x3e38aa3b, v75
	v_max3_f32 v34, v34, v86, v87
	v_cndmask_b32_e64 v90, v238, v43, s[8:9]
	v_cndmask_b32_e64 v91, v238, v44, s[8:9]
	v_fmac_f32_e32 v45, 0x3e38aa3b, v76
	v_fmac_f32_e32 v46, 0x3e38aa3b, v77
	v_max3_f32 v34, v34, v88, v89
	v_cndmask_b32_e64 v92, v238, v45, s[8:9]
	v_cndmask_b32_e64 v93, v238, v46, s[8:9]
	v_fmac_f32_e32 v47, 0x3e38aa3b, v78
	v_fmac_f32_e32 v48, 0x3e38aa3b, v79
	v_max3_f32 v34, v34, v90, v91
	v_cndmask_b32_e64 v94, v238, v47, s[8:9]
	v_cndmask_b32_e64 v95, v238, v48, s[8:9]
	v_fmac_f32_e32 v49, 0x3e38aa3b, v80
	v_max3_f32 v34, v34, v92, v93
	v_cndmask_b32_e64 v96, v238, v49, s[8:9]
	v_max3_f32 v34, v34, v94, v95
	v_max3_f32 v34, v34, v96, v97
	v_mov_b32_e32 v35, v34
	s_nop 1
	v_permlane32_swap_b32_e32 v34, v35
	v_max_f32_e32 v35, v35, v35
	v_max_f32_e32 v34, v34, v34
	v_max_f32_e32 v34, v34, v35
	v_cmp_gt_f32_e32 vcc, v34, v0
	v_mov_b32_e32 v162, v195
	s_nop 0
	v_cndmask_b32_e32 v194, v231, v34, vcc
	s_cbranch_vccz .LBB0_670
	v_sub_f32_e32 v34, v231, v194
	v_exp_f32_e32 v34, v34
	s_nop 0
	v_mul_f32_e32 v162, v195, v34
	v_pk_mul_f32 v[32:33], v[32:33], v[34:35] op_sel_hi:[1,0]
	v_pk_mul_f32 v[30:31], v[30:31], v[34:35] op_sel_hi:[1,0]
	v_pk_mul_f32 v[28:29], v[28:29], v[34:35] op_sel_hi:[1,0]
	v_pk_mul_f32 v[26:27], v[26:27], v[34:35] op_sel_hi:[1,0]
	v_pk_mul_f32 v[24:25], v[24:25], v[34:35] op_sel_hi:[1,0]
	v_pk_mul_f32 v[22:23], v[22:23], v[34:35] op_sel_hi:[1,0]
	v_pk_mul_f32 v[20:21], v[20:21], v[34:35] op_sel_hi:[1,0]
	v_pk_mul_f32 v[16:17], v[16:17], v[34:35] op_sel_hi:[1,0]
	v_pk_mul_f32 v[14:15], v[14:15], v[34:35] op_sel_hi:[1,0]
	v_pk_mul_f32 v[12:13], v[12:13], v[34:35] op_sel_hi:[1,0]
	v_pk_mul_f32 v[10:11], v[10:11], v[34:35] op_sel_hi:[1,0]
	v_pk_mul_f32 v[8:9], v[8:9], v[34:35] op_sel_hi:[1,0]
	v_pk_mul_f32 v[6:7], v[6:7], v[34:35] op_sel_hi:[1,0]
	v_pk_mul_f32 v[4:5], v[4:5], v[34:35] op_sel_hi:[1,0]
	v_pk_mul_f32 v[18:19], v[18:19], v[34:35] op_sel_hi:[1,0]
	v_pk_mul_f32 v[2:3], v[2:3], v[34:35] op_sel_hi:[1,0]

; __device__ __forceinline__ float pair_max(float v) { auto r = __builtin_amdgcn_permlane32_swap(__float_as_uint(v), __float_as_uint(v), false, false); return fmaxf(__uint_as_float(r[0]), __uint_as_float(r[1])); }
; template <bool CAUSAL> __device__ __forceinline__ void moba_span(lbyte* kbuf, lbyte* vbuf, const bf16* Kh, const bf16* Vh, int kpos0, int nsub, const s16x8* qf, int tq, bool valid, int qlo, int qhi, ...
;     ...
;         if (!CAUSAL && bmax - bmin <= 1) {
;             const float t0 = tab[bmin], t1 = tab[bmax]; const int th1 = thr[bmax];
;             float mxr = s[0][0];
; #pragma unroll
;             for (int r = 1; r < 16; ++r) mxr = fmaxf(mxr, s[0][r]);
;             mxr = pair_max(mxr);
;             const float cL = valid ? 0.125f * LOG2E : 0.f, bL = valid ? t0 : -INFINITY, mx = valid ? mxr * (0.125f * LOG2E) + fmaxf(t0, t1) : -INFINITY;
;             const bool grow = mx > m + 8.0f; const float mn = grow ? mx : m, off = bL - mn, offB = off + (t1 - t0);
;             if (__any(grow)) { const float alpha = __builtin_amdgcn_exp2f(m - mn); l *= alpha; o[0] = o[0] * alpha; o[1] = o[1] * alpha; }
;             m = mn;
.LBB0_671:
	s_and_b64 vcc, exec, s[24:25]
	s_cbranch_vccz .LBB0_675
	s_lshl_b32 s21, s15, 2
	s_add_i32 s23, 0, 0x23f50
	s_add_i32 s21, s23, s21
	v_mov_b32_e32 v34, s21
	s_lshl_b32 s21, s17, 2
	s_add_i32 s23, s23, s21
	s_add_i32 s21, s21, 0
	s_add_i32 s21, s21, 0x23fd0
	v_mov_b32_e32 v36, s23
	v_mov_b32_e32 v37, s21
	ds_read_b32 v35, v34
	ds_read_b32 v36, v36
	ds_read_b32 v34, v37
	v_max_f32_e32 v37, v66, v67
	v_max3_f32 v37, v37, v68, v69
	v_max3_f32 v37, v37, v70, v71
	v_max3_f32 v37, v37, v72, v73
	v_max3_f32 v37, v37, v74, v75
	v_max3_f32 v37, v37, v76, v77
	v_max3_f32 v37, v37, v78, v79
	v_max3_f32 v37, v37, v80, v81
	v_mov_b32_e32 v38, v37
	s_nop 1
	v_permlane32_swap_b32_e32 v37, v38
	v_max_f32_e32 v37, v37, v38
	s_waitcnt lgkmcnt(1)
	v_max_f32_e32 v38, v35, v36
	v_fmac_f32_e32 v38, 0x3e38aa3b, v37
	v_cndmask_b32_e64 v37, v238, v38, s[8:9]
	v_cmp_gt_f32_e32 vcc, v37, v0
	s_nop 1
	v_cndmask_b32_e32 v194, v231, v37, vcc
	s_cbranch_vccz .LBB0_674
	v_sub_f32_e32 v0, v231, v194
	v_exp_f32_e32 v0, v0
	s_nop 0
	v_mul_f32_e32 v195, v195, v0
	v_pk_mul_f32 v[32:33], v[32:33], v[0:1] op_sel_hi:[1,0]
	v_pk_mul_f32 v[30:31], v[30:31], v[0:1] op_sel_hi:[1,0]
	v_pk_mul_f32 v[28:29], v[28:29], v[0:1] op_sel_hi:[1,0]
	v_pk_mul_f32 v[26:27], v[26:27], v[0:1] op_sel_hi:[1,0]
	v_pk_mul_f32 v[24:25], v[24:25], v[0:1] op_sel_hi:[1,0]
	v_pk_mul_f32 v[22:23], v[22:23], v[0:1] op_sel_hi:[1,0]
	v_pk_mul_f32 v[20:21], v[20:21], v[0:1] op_sel_hi:[1,0]
	v_pk_mul_f32 v[16:17], v[16:17], v[0:1] op_sel_hi:[1,0]
	v_pk_mul_f32 v[14:15], v[14:15], v[0:1] op_sel_hi:[1,0]
	v_pk_mul_f32 v[12:13], v[12:13], v[0:1] op_sel_hi:[1,0]
	v_pk_mul_f32 v[10:11], v[10:11], v[0:1] op_sel_hi:[1,0]
	v_pk_mul_f32 v[8:9], v[8:9], v[0:1] op_sel_hi:[1,0]
	v_pk_mul_f32 v[6:7], v[6:7], v[0:1] op_sel_hi:[1,0]
	v_pk_mul_f32 v[4:5], v[4:5], v[0:1] op_sel_hi:[1,0]
	v_pk_mul_f32 v[18:19], v[18:19], v[0:1] op_sel_hi:[1,0]
	v_pk_mul_f32 v[2:3], v[2:3], v[0:1] op_sel_hi:[1,0]

; __device__ __forceinline__ unsigned pk2(float lo, float hi) { f32x2_t v = {lo, hi}; bf16x2_t b = __builtin_convertvector(v, bf16x2_t); return __builtin_bit_cast(unsigned, b); }
; #define MFMA32(a, b, c) __builtin_amdgcn_mfma_f32_32x32x16_bf16(a, b, c, 0, 0, 0)
; template <int DT> __device__ __forceinline__ void pv1(f32x16* o, const s16x8* vf, s16x8 p0, s16x8 p1) {
; #pragma unroll
;     for (int dt = 0; dt < DT; ++dt) o[dt] = MFMA32(vf[dt * 2], p0, o[dt]);
; #pragma unroll
;     for (int dt = 0; dt < DT; ++dt) o[dt] = MFMA32(vf[dt * 2 + 1], p1, o[dt]);
; }
; __device__ __forceinline__ void pack_p_nat(const f32x16& s, s16x8& p0, s16x8& p1) {
;     unsigned a0 = pk2(s[0], s[1]), a1 = pk2(s[2], s[3]), b0 = pk2(s[4], s[5]), b1 = pk2(s[6], s[7]);
;     unsigned c0 = pk2(s[8], s[9]), c1 = pk2(s[10], s[11]), d0 = pk2(s[12], s[13]), d1 = pk2(s[14], s[15]);
;     { auto r = __builtin_amdgcn_permlane32_swap(a0, b0, false, false); a0 = r[0]; b0 = r[1]; }
;     { auto r = __builtin_amdgcn_permlane32_swap(a1, b1, false, false); a1 = r[0]; b1 = r[1]; }
;     { auto r = __builtin_amdgcn_permlane32_swap(c0, d0, false, false); c0 = r[0]; d0 = r[1]; }
;     { auto r = __builtin_amdgcn_permlane32_swap(c1, d1, false, false); c1 = r[0]; d1 = r[1]; }
;     p0 = __builtin_bit_cast(s16x8, (u32x4){a0, a1, b0, b1}); p1 = __builtin_bit_cast(s16x8, (u32x4){c0, c1, d0, d1});
; }
.LBB0_675:
	v_cvt_pk_bf16_f32 v34, v82, v83
	v_cvt_pk_bf16_f32 v35, v84, v85
	v_cvt_pk_bf16_f32 v36, v86, v87
	v_cvt_pk_bf16_f32 v37, v88, v89
	s_nop 0
	v_permlane32_swap_b32_e32 v34, v36
	v_permlane32_swap_b32_e32 v35, v37
	v_cvt_pk_bf16_f32 v66, v90, v91
	s_waitcnt lgkmcnt(6)
	v_mfma_f32_32x32x16_bf16 v[2:17], v[158:161], v[34:37], v[2:17]
	v_cvt_pk_bf16_f32 v67, v92, v93
	v_cvt_pk_bf16_f32 v68, v94, v95
	v_cvt_pk_bf16_f32 v69, v96, v97
	s_nop 0
	v_permlane32_swap_b32_e32 v66, v68
	v_permlane32_swap_b32_e32 v67, v69
	s_waitcnt lgkmcnt(4)
	v_mfma_f32_32x32x16_bf16 v[18:33], v[154:157], v[34:37], v[18:33]
	s_waitcnt lgkmcnt(2)
	v_mfma_f32_32x32x16_bf16 v[2:17], v[150:153], v[66:69], v[2:17]
	v_add_f32_e32 v0, v230, v163
	s_sub_i32 s11, s11, 32
	s_add_i32 s22, s22, 32
	v_add_f32_e32 v195, v162, v0
	s_cmpk_lg_i32 s11, 0xff00
	s_waitcnt lgkmcnt(0)
	v_mfma_f32_32x32x16_bf16 v[18:33], v[146:149], v[66:69], v[18:33]
	s_cbranch_scc0 .LBB0_677
	v_mov_b32_e32 v231, v194
	s_nop 2
	s_branch .LBB0_665

; #define LAS __attribute__((address_space(3)))
; __device__ __forceinline__ unsigned pk2(float lo, float hi) { f32x2_t v = {lo, hi}; bf16x2_t b = __builtin_convertvector(v, bf16x2_t); return __builtin_bit_cast(unsigned, b); }
; __device__ __forceinline__ void cross_unit(lbyte* lds, bf16* CQ, const bf16* CKV, const float* gq, const float* gk, int layer, int b, int hc, int qblk0, int qstep, int nq) {
;     ...
; #pragma unroll 4
;     for (int i = tid; i < 256 * 16; i += NT) { const int row = i >> 4, ch = i & 15; const bf16* src = CKV + (size_t)(b * MEMLEN + row) * LDK;
;         const u32x4 kv = *(const u32x4*)(src + kcol + ch * 8), vv = *(const u32x4*)(src + vcol + ch * 8);
;         { float f[8]; f[0] = __uint_as_float(kv.x << 16); f[1] = __uint_as_float(kv.x & 0xffff0000u); f[2] = __uint_as_float(kv.y << 16); f[3] = __uint_as_float(kv.y & 0xffff0000u);
;           f[4] = __uint_as_float(kv.z << 16); f[5] = __uint_as_float(kv.z & 0xffff0000u); f[6] = __uint_as_float(kv.w << 16); f[7] = __uint_as_float(kv.w & 0xffff0000u);
;           float ss = (f[0] * f[0] + f[1] * f[1]) + (f[2] * f[2] + f[3] * f[3]) + (f[4] * f[4] + f[5] * f[5]) + (f[6] * f[6] + f[7] * f[7]);
;           ss = pg8::row16_sum(ss); const float rn = __builtin_amdgcn_rsqf(ss * (1.0f / 128.0f) + 1e-6f);
;           const f32x4 ga = *(const f32x4*)(gk + ch * 8), gb = *(const f32x4*)(gk + ch * 8 + 4);
;           u32x4 kn; kn.x = pk2(f[0] * rn * ga[0], f[1] * rn * ga[1]); kn.y = pk2(f[2] * rn * ga[2], f[3] * rn * ga[3]); kn.z = pk2(f[4] * rn * gb[0], f[5] * rn * gb[1]); kn.w = pk2(f[6] * rn * gb[2], f[7] * rn * gb[3]);
;           *(LAS u32x4*)(lds + CX_K + row * CX_KP + ch * 16) = kn; }
;         LAS unsigned short* vp = (LAS unsigned short*)(lds + CX_V + (ch * 8) * CX_VP + row * 2);
;         vp[0 * (CX_VP / 2)] = (unsigned short)(vv.x & 0xffffu); vp[1 * (CX_VP / 2)] = (unsigned short)(vv.x >> 16); vp[2 * (CX_VP / 2)] = (unsigned short)(vv.y & 0xffffu); vp[3 * (CX_VP / 2)] = (unsigned short)(vv.y >> 16);
;         vp[4 * (CX_VP / 2)] = (unsigned short)(vv.z & 0xffffu); vp[5 * (CX_VP / 2)] = (unsigned short)(vv.z >> 16); vp[6 * (CX_VP / 2)] = (unsigned short)(vv.w & 0xffffu); vp[7 * (CX_VP / 2)] = (unsigned short)(vv.w >> 16); }
.LBB0_980:
.LBB0_981:
	s_and_b64 vcc, exec, s[70:71]
	s_cbranch_vccnz .LBB0_993
	v_mov_b32_e32 v0, s42
	ds_read_b64 v[2:3], v0
	v_readlane_b32 s0, v255, 21
	s_lshl_b32 s86, s74, 7
	s_waitcnt lgkmcnt(0)
	v_readfirstlane_b32 s4, v3
	v_mov_b32_e32 v0, s0
	v_readfirstlane_b32 s5, v2
	ds_read_b128 v[2:5], v0
	s_movk_i32 s0, 0x1000
	s_waitcnt lgkmcnt(0)
	v_readfirstlane_b32 s6, v5
	v_mov_b32_e32 v5, v232
	v_readfirstlane_b32 s8, v3
	v_readfirstlane_b32 s9, v2
	v_readfirstlane_b32 s7, v4
	s_nop 0
	v_readfirstlane_b32 s10, v5
	v_cmp_gt_i32_e32 vcc, s0, v5
	s_and_saveexec_b64 s[0:1], vcc
	s_cbranch_execz .LBB0_985
	s_lshl_b64 s[12:13], s[86:87], 2
	s_add_u32 s12, s7, s12
	s_addc_u32 s13, s6, s13
	s_add_u32 s11, s5, 0x1cc00000
	s_addc_u32 s14, s4, 0
	s_lshl_b32 s6, s74, 10
	v_readlane_b32 s16, v254, 16
	s_add_i32 s6, s6, s16
	s_ashr_i32 s7, s6, 31
	s_lshl_b64 s[6:7], s[6:7], 1
	v_and_b32_e32 v6, 15, v5
	s_add_u32 s6, s11, s6
	v_lshlrev_b32_e32 v0, 5, v6
	v_readlane_b32 s11, v255, 22
	s_addc_u32 s7, s14, s7
	v_lshl_add_u64 v[2:3], s[12:13], 0, v[0:1]
	v_lshlrev_b32_e32 v0, 4, v6
	v_mov_b32_e32 v7, s11
	s_movk_i32 s11, 0x1080
	v_add_u32_e32 v4, 0, v0
	v_mad_u32_u24 v8, v6, s11, v7
	v_lshl_add_u64 v[6:7], s[6:7], 0, v[0:1]
	s_mov_b64 s[6:7], 0
	v_mov_b32_e32 v0, v5
	v_readlane_b32 s17, v254, 17
	global_load_dwordx4 v[200:203], v[2:3], off offset:16
	global_load_dwordx4 v[204:207], v[2:3], off
	v_mov_b32_e32 v198, 0x40000
	v_mov_b32_e32 v199, 0
	v_ashrrev_i32_e32 v9, 4, v0
	v_add_u32_e32 v10, s33, v9
	v_ashrrev_i32_e32 v11, 31, v10
	v_lshlrev_b64 v[10:11], 13, v[10:11]
	v_lshl_add_u64 v[196:197], v[6:7], 0, v[10:11]
	global_load_dwordx4 v[208:211], v[196:197], off
	global_load_dwordx4 v[212:215], v[196:197], off offset:1024
.LBB0_984:
	v_ashrrev_i32_e32 v9, 4, v0
	v_cmp_lt_i32_e32 vcc, s61, v0
	s_or_b64 s[6:7], vcc, s[6:7]
	s_waitcnt vmcnt(1)
	v_and_b32_e32 v23, 0xffff0000, v211
	v_and_b32_e32 v25, 0xffff0000, v210
	v_lshlrev_b32_e32 v22, 16, v211
	v_lshlrev_b32_e32 v24, 16, v210
	v_mov_b32_e32 v16, v23
	v_mov_b32_e32 v17, v25
	v_mov_b32_e32 v12, v22
	v_mov_b32_e32 v13, v24
	v_pk_mul_f32 v[16:17], v[16:17], v[16:17]
	v_and_b32_e32 v27, 0xffff0000, v209
	v_and_b32_e32 v29, 0xffff0000, v208
	v_pk_fma_f32 v[12:13], v[12:13], v[12:13], v[16:17]
	v_lshlrev_b32_e32 v26, 16, v209
	v_lshlrev_b32_e32 v28, 16, v208
	v_lshl_add_u64 v[196:197], v[196:197], 0, v[198:199]
	global_load_dwordx4 v[208:211], v[196:197], off
	v_mov_b32_e32 v16, v29
	v_mov_b32_e32 v17, v27
	v_mov_b32_e32 v10, v28
	v_mov_b32_e32 v11, v26
	v_pk_mul_f32 v[16:17], v[16:17], v[16:17]
	s_nop 0
	v_pk_fma_f32 v[10:11], v[10:11], v[10:11], v[16:17]
	s_nop 0
	v_add_f32_e32 v10, v10, v11
	v_add_f32_e32 v10, v13, v10
	v_add_f32_e32 v16, v12, v10
	s_nop 1
	v_add_f32_dpp v16, v16, v16 row_ror:8 row_mask:0xf bank_mask:0xf
	s_nop 1
	v_add_f32_dpp v16, v16, v16 row_ror:4 row_mask:0xf bank_mask:0xf
	s_nop 1
	v_add_f32_dpp v16, v16, v16 row_ror:2 row_mask:0xf bank_mask:0xf
	s_nop 1
	v_add_f32_dpp v16, v16, v16 row_ror:1 row_mask:0xf bank_mask:0xf
	s_nop 0
	v_fmamk_f32 v14, v16, 0x3c000000, v233
	v_rsq_f32_e32 v30, v14
	s_nop 0
	v_pk_mul_f32 v[28:29], v[30:31], v[28:29] op_sel_hi:[0,1]
	v_pk_mul_f32 v[26:27], v[30:31], v[26:27] op_sel_hi:[0,1]
	v_pk_mul_f32 v[18:19], v[204:205], v[28:29]
	v_pk_mul_f32 v[20:21], v[206:207], v[26:27]
	v_cvt_pk_bf16_f32 v18, v18, v19
	v_cvt_pk_bf16_f32 v19, v20, v21
	v_pk_mul_f32 v[20:21], v[30:31], v[24:25] op_sel_hi:[0,1]
	v_pk_mul_f32 v[14:15], v[200:201], v[20:21]
	s_nop 0
	v_cvt_pk_bf16_f32 v20, v14, v15
	v_pk_mul_f32 v[14:15], v[30:31], v[22:23] op_sel_hi:[0,1]
	v_pk_mul_f32 v[14:15], v[202:203], v[14:15]
	s_nop 0
	v_cvt_pk_bf16_f32 v21, v14, v15
	v_mad_u64_u32 v[14:15], s[12:13], v9, s29, v[4:5]
	v_lshl_add_u32 v9, v9, 1, v8
	ds_write_b128 v14, v[18:21]
	s_waitcnt vmcnt(1)
	ds_write_b16 v9, v212
	ds_write_b16_d16_hi v9, v212 offset:528
	ds_write_b16 v9, v213 offset:1056
	ds_write_b16_d16_hi v9, v213 offset:1584
	ds_write_b16 v9, v214 offset:2112
	ds_write_b16_d16_hi v9, v214 offset:2640
	ds_write_b16 v9, v215 offset:3168
	ds_write_b16_d16_hi v9, v215 offset:3696
	v_add_u32_e32 v9, 0x200, v0
	v_mov_b32_e32 v0, v9
	global_load_dwordx4 v[212:215], v[196:197], off offset:1024
	s_andn2_b64 exec, exec, s[6:7]
	s_cbranch_execnz .LBB0_984

;     __device__ __forceinline__ void operator()(f32x4 (&acc)[2][2][4][2], const Unit& u, int ui, int wr, int wc, int fr_, int fq_) const {
;     ...
; #pragma unroll
;         for (int ai = 0; ai < 2; ++ai)
; #pragma unroll
;             for (int m = 0; m < 4; ++m) { const float r = rtab[ui * 256 + ai * HALF + wr * 64 + m * 16 + fr];
; #pragma unroll
;                 for (int bj = 0; bj < 2; ++bj)
; #pragma unroll
;                     for (int n = 0; n < 2; ++n) acc[ai][bj][m][n] = acc[ai][bj][m][n] * r; }
;         const int fbase = u.pn * 128 + 32 * wc + 8 * fq;
;         if (wr == 0 && fr < 2) {
; #pragma unroll
;             for (int bj = 0; bj < 2; ++bj)
; #pragma unroll
;                 for (int n = 0; n < 2; ++n) *(f32x4*)(halo + (size_t)(u.pm * 4 + fr) * 5632 + bj * 2816 + fbase + 4 * n) = acc[0][bj][0][n];
;         }
.LBB0_1178:
	s_mov_b32 s98, 0xbfb8aa3b
	s_lshl_b32 s0, s13, 10
	v_mov_b32_e32 v132, v207
	v_mov_b32_e32 v210, v206
	s_add_i32 s0, s94, s0
	s_nop 0
	v_lshl_add_u32 v133, v210, 2, s0
	ds_read2_b32 v[130:131], v133 offset1:16
	ds_read2_b32 v[192:193], v133 offset0:128 offset1:144
	ds_read2_b32 v[196:197], v133 offset0:32 offset1:48
	ds_read2_b32 v[188:189], v133 offset0:160 offset1:176
	s_lshl_b32 s0, s12, 7
	s_or_b32 s0, s0, s69
	v_lshlrev_b32_e32 v143, 3, v132
	v_add_u32_e32 v186, s0, v143
	v_cmp_gt_i32_e32 vcc, 2, v210
	s_waitcnt lgkmcnt(0)
	v_mov_b32_e32 v194, v131
	v_pk_mul_f32 v[140:141], v[128:129], v[130:131] op_sel_hi:[1,0]
	v_pk_mul_f32 v[138:139], v[126:127], v[130:131] op_sel_hi:[1,0]
	v_pk_mul_f32 v[124:125], v[124:125], v[130:131] op_sel_hi:[1,0]
	v_pk_mul_f32 v[122:123], v[122:123], v[130:131] op_sel_hi:[1,0]
	v_pk_mul_f32 v[88:89], v[88:89], v[130:131] op_sel_hi:[1,0]
	v_pk_mul_f32 v[86:87], v[86:87], v[130:131] op_sel_hi:[1,0]
	v_pk_mul_f32 v[60:61], v[60:61], v[130:131] op_sel_hi:[1,0]
	v_pk_mul_f32 v[58:59], v[58:59], v[130:131] op_sel_hi:[1,0]
	v_mov_b32_e32 v190, v193
	s_and_b64 s[4:5], s[50:51], vcc
	v_ashrrev_i32_e32 v187, 31, v186
	s_and_saveexec_b64 s[0:1], s[4:5]
	s_cbranch_execz .LBB0_1180
	v_lshl_add_u32 v128, s76, 2, v210
	v_mov_b64_e32 v[126:127], s[48:49]
	s_movk_i32 s4, 0x5800
	v_mad_i64_i32 v[126:127], s[4:5], v128, s4, v[126:127]
	v_lshl_add_u64 v[126:127], v[186:187], 2, v[126:127]
	global_store_dwordx4 v[126:127], v[138:141], off
	global_store_dwordx4 v[126:127], v[122:125], off offset:16
	v_add_co_u32_e32 v126, vcc, 0x2000, v126
	s_nop 1
	v_addc_co_u32_e32 v127, vcc, 0, v127, vcc
	global_store_dwordx4 v[126:127], v[86:89], off offset:3072
	global_store_dwordx4 v[126:127], v[58:61], off offset:3088

; #define PG8_LAS __attribute__((address_space(3)))
;     __device__ __forceinline__ void operator()(f32x4 (&acc)[2][2][4][2], const Unit& u, int ui, int wr, int wc, int fr_, int fq_) const {
;     ...
;         for (int ai = 0; ai < 2; ++ai)
; #pragma unroll
;             for (int m = 0; m < 4; ++m) { const float r = rtab[ui * 256 + ai * HALF + wr * 64 + m * 16 + fr];
; #pragma unroll
;                 for (int bj = 0; bj < 2; ++bj)
; #pragma unroll
;                     for (int n = 0; n < 2; ++n) acc[ai][bj][m][n] = acc[ai][bj][m][n] * r; }
;     ...
;         for (int bj = 0; bj < 2; ++bj)
; #pragma unroll
;             for (int n = 0; n < 2; ++n) { const int ch = bj * 2816 + fbase + 4 * n;
;                 const f32x4 w0 = *(const f32x4*)(cw + ch), w1 = *(const f32x4*)(cw + 5632 + ch), w2 = *(const f32x4*)(cw + 2 * 5632 + ch), bb = *(const f32x4*)(cb + ch);
; #pragma unroll
;                 for (int ai = 0; ai < 2; ++ai) { const int kb = 2 * ai + wr;
;                     f32x4 c62 = (f32x4){0.f, 0.f, 0.f, 0.f}, c63 = c62;
;                     if (kb > 0) { c62 = *(const PG8_LAS f32x4*)(exch + (((kb - 1) * 2 + 0) * 256 + bj * HALF + 32 * wc + 8 * fq + 4 * n)); c63 = *(const PG8_LAS f32x4*)(exch + (((kb - 1) * 2 + 1) * 256 + bj * HALF + 32 * wc + 8 * fq + 4 * n)); }
; #pragma unroll
;                     for (int m = 3; m >= 0; --m) { f32x4 cur = acc[ai][bj][m][n], res;
; #pragma unroll
;                         for (int j = 0; j < 4; ++j) { const float c = cur[j]; const float pv = (m > 0) ? acc[ai][bj][m > 0 ? m - 1 : 0][n][j] : (fr == 15 ? c63[j] : c62[j]); float t1, t2;
;                             asm volatile("s_nop 1\n\tv_mov_b32_dpp %0, %3 row_ror:1 row_mask:0xf bank_mask:0xf\n\tv_mov_b32_dpp %1, %3 row_ror:2 row_mask:0xf bank_mask:0xf\n\t"
;                                          "v_mov_b32_dpp %0, %2 row_shr:1 row_mask:0xf bank_mask:0xf\n\tv_mov_b32_dpp %1, %2 row_shr:2 row_mask:0xf bank_mask:0xf"
;                                          : "=&v"(t1), "=&v"(t2) : "v"(c), "v"(pv));
;                             res[j] = bb[j] + w0[j] * t2 + w1[j] * t1 + w2[j] * c; }
;                         asm volatile("" : "+v"(res[0]), "+v"(res[1]), "+v"(res[2]), "+v"(res[3]));
;                         acc[ai][bj][m][n] = res; } }
.LBB0_1190:
	v_mov_b32_e32 v30, v194
	v_mov_b32_e32 v31, v194
	v_mov_b32_e32 v197, v196
	v_pk_mul_f32 v[30:31], v[80:81], v[30:31]
	v_pk_mul_f32 v[76:77], v[76:77], v[196:197] op_sel_hi:[1,0]
	v_pk_mul_f32 v[74:75], v[74:75], v[196:197]
	v_mov_b32_e32 v195, v194
	v_pk_mul_f32 v[78:79], v[78:79], v[194:195]
	s_waitcnt vmcnt(0)
	v_mov_b32_e32 v133, v248
	v_fmac_f32_dpp v133, v110, v234 row_shr:2 row_mask:0xf bank_mask:0xf
	v_fmac_f32_dpp v133, v74, v234 row_shl:14 row_mask:0xf bank_mask:0xf
	v_fmac_f32_dpp v133, v110, v240 row_shr:1 row_mask:0xf bank_mask:0xf
	v_fmac_f32_dpp v133, v74, v240 row_shl:15 row_mask:0xf bank_mask:0xf
	v_fmac_f32_e32 v133, v110, v244
	v_mov_b32_e32 v131, v249
	v_fmac_f32_dpp v131, v111, v235 row_shr:2 row_mask:0xf bank_mask:0xf
	v_fmac_f32_dpp v131, v75, v235 row_shl:14 row_mask:0xf bank_mask:0xf
	v_fmac_f32_dpp v131, v111, v241 row_shr:1 row_mask:0xf bank_mask:0xf
	v_fmac_f32_dpp v131, v75, v241 row_shl:15 row_mask:0xf bank_mask:0xf
	v_fmac_f32_e32 v131, v111, v245
	v_mov_b32_e32 v132, v250
	v_fmac_f32_dpp v132, v112, v236 row_shr:2 row_mask:0xf bank_mask:0xf
	v_fmac_f32_dpp v132, v76, v236 row_shl:14 row_mask:0xf bank_mask:0xf
	v_fmac_f32_dpp v132, v112, v242 row_shr:1 row_mask:0xf bank_mask:0xf
	v_fmac_f32_dpp v132, v76, v242 row_shl:15 row_mask:0xf bank_mask:0xf
	v_fmac_f32_e32 v132, v112, v246
	v_mov_b32_e32 v135, v251
	v_fmac_f32_dpp v135, v113, v237 row_shr:2 row_mask:0xf bank_mask:0xf
	v_fmac_f32_dpp v135, v77, v237 row_shl:14 row_mask:0xf bank_mask:0xf
	v_fmac_f32_dpp v135, v113, v243 row_shr:1 row_mask:0xf bank_mask:0xf
	v_fmac_f32_dpp v135, v77, v243 row_shl:15 row_mask:0xf bank_mask:0xf
	v_fmac_f32_e32 v135, v113, v247
	s_and_b64 vcc, exec, s[12:13]
	v_mov_b32_e32 v142, v248
	v_fmac_f32_dpp v142, v74, v234 row_shr:2 row_mask:0xf bank_mask:0xf
	v_fmac_f32_dpp v142, v78, v234 row_shl:14 row_mask:0xf bank_mask:0xf
	v_fmac_f32_dpp v142, v74, v240 row_shr:1 row_mask:0xf bank_mask:0xf
	v_fmac_f32_dpp v142, v78, v240 row_shl:15 row_mask:0xf bank_mask:0xf
	v_fmac_f32_e32 v142, v74, v244
	v_mov_b32_e32 v107, 0
	v_mov_b32_e32 v136, v249
	v_fmac_f32_dpp v136, v75, v235 row_shr:2 row_mask:0xf bank_mask:0xf
	v_fmac_f32_dpp v136, v79, v235 row_shl:14 row_mask:0xf bank_mask:0xf
	v_fmac_f32_dpp v136, v75, v241 row_shr:1 row_mask:0xf bank_mask:0xf
	v_fmac_f32_dpp v136, v79, v241 row_shl:15 row_mask:0xf bank_mask:0xf
	v_fmac_f32_e32 v136, v75, v245
	v_mov_b32_e32 v108, 0
	v_mov_b32_e32 v137, v250
	v_fmac_f32_dpp v137, v76, v236 row_shr:2 row_mask:0xf bank_mask:0xf
	v_fmac_f32_dpp v137, v30, v236 row_shl:14 row_mask:0xf bank_mask:0xf
	v_fmac_f32_dpp v137, v76, v242 row_shr:1 row_mask:0xf bank_mask:0xf
	v_fmac_f32_dpp v137, v30, v242 row_shl:15 row_mask:0xf bank_mask:0xf
	v_fmac_f32_e32 v137, v76, v246
	v_mov_b32_e32 v143, v251
	v_fmac_f32_dpp v143, v77, v237 row_shr:2 row_mask:0xf bank_mask:0xf
	v_fmac_f32_dpp v143, v31, v237 row_shl:14 row_mask:0xf bank_mask:0xf
	v_fmac_f32_dpp v143, v77, v243 row_shr:1 row_mask:0xf bank_mask:0xf
	v_fmac_f32_dpp v143, v31, v243 row_shl:15 row_mask:0xf bank_mask:0xf
	v_fmac_f32_e32 v143, v77, v247
	v_mov_b32_e32 v109, 0
	v_mov_b32_e32 v225, v248
	v_fmac_f32_dpp v225, v78, v234 row_shr:2 row_mask:0xf bank_mask:0xf
	v_fmac_f32_dpp v225, v122, v234 row_shl:14 row_mask:0xf bank_mask:0xf
	v_fmac_f32_dpp v225, v78, v240 row_shr:1 row_mask:0xf bank_mask:0xf
	v_fmac_f32_dpp v225, v122, v240 row_shl:15 row_mask:0xf bank_mask:0xf
	v_fmac_f32_e32 v225, v78, v244
	v_mov_b32_e32 v144, v249
	v_fmac_f32_dpp v144, v79, v235 row_shr:2 row_mask:0xf bank_mask:0xf
	v_fmac_f32_dpp v144, v123, v235 row_shl:14 row_mask:0xf bank_mask:0xf
	v_fmac_f32_dpp v144, v79, v241 row_shr:1 row_mask:0xf bank_mask:0xf
	v_fmac_f32_dpp v144, v123, v241 row_shl:15 row_mask:0xf bank_mask:0xf
	v_fmac_f32_e32 v144, v79, v245
	v_mov_b32_e32 v145, v250
	v_fmac_f32_dpp v145, v30, v236 row_shr:2 row_mask:0xf bank_mask:0xf
	v_fmac_f32_dpp v145, v124, v236 row_shl:14 row_mask:0xf bank_mask:0xf
	v_fmac_f32_dpp v145, v30, v242 row_shr:1 row_mask:0xf bank_mask:0xf
	v_fmac_f32_dpp v145, v124, v242 row_shl:15 row_mask:0xf bank_mask:0xf
	v_fmac_f32_e32 v145, v30, v246
	s_waitcnt lgkmcnt(0)
	v_cndmask_b32_e64 v75, v118, v126, s[8:9]
	v_mov_b32_e32 v226, v251
	v_fmac_f32_dpp v226, v31, v237 row_shr:2 row_mask:0xf bank_mask:0xf
	v_fmac_f32_dpp v226, v125, v237 row_shl:14 row_mask:0xf bank_mask:0xf
	v_fmac_f32_dpp v226, v31, v243 row_shr:1 row_mask:0xf bank_mask:0xf
	v_fmac_f32_dpp v226, v125, v243 row_shl:15 row_mask:0xf bank_mask:0xf
	v_fmac_f32_e32 v226, v31, v247
	v_cndmask_b32_e64 v74, v119, v127, s[8:9]
	v_mov_b32_e32 v126, v248
	v_fmac_f32_dpp v126, v122, v234 row_shr:2 row_mask:0xf bank_mask:0xf
	v_fmac_f32_dpp v126, v75, v234 row_shl:14 row_mask:0xf bank_mask:0xf
	v_fmac_f32_dpp v126, v122, v240 row_shr:1 row_mask:0xf bank_mask:0xf
	v_fmac_f32_dpp v126, v75, v240 row_shl:15 row_mask:0xf bank_mask:0xf
	v_fmac_f32_e32 v126, v122, v244
	v_cndmask_b32_e64 v31, v120, v128, s[8:9]
	v_mov_b32_e32 v122, v249
	v_fmac_f32_dpp v122, v123, v235 row_shr:2 row_mask:0xf bank_mask:0xf
	v_fmac_f32_dpp v122, v74, v235 row_shl:14 row_mask:0xf bank_mask:0xf
	v_fmac_f32_dpp v122, v123, v241 row_shr:1 row_mask:0xf bank_mask:0xf
	v_fmac_f32_dpp v122, v74, v241 row_shl:15 row_mask:0xf bank_mask:0xf
	v_fmac_f32_e32 v122, v123, v245
	v_cndmask_b32_e64 v30, v121, v129, s[8:9]
	v_mov_b32_e32 v123, v250
	v_fmac_f32_dpp v123, v124, v236 row_shr:2 row_mask:0xf bank_mask:0xf
	v_fmac_f32_dpp v123, v31, v236 row_shl:14 row_mask:0xf bank_mask:0xf
	v_fmac_f32_dpp v123, v124, v242 row_shr:1 row_mask:0xf bank_mask:0xf
	v_fmac_f32_dpp v123, v31, v242 row_shl:15 row_mask:0xf bank_mask:0xf
	v_fmac_f32_e32 v123, v124, v246
	v_mov_b32_e32 v75, 0
	v_mov_b32_e32 v124, v251
	v_fmac_f32_dpp v124, v125, v237 row_shr:2 row_mask:0xf bank_mask:0xf
	v_fmac_f32_dpp v124, v30, v237 row_shl:14 row_mask:0xf bank_mask:0xf
	v_fmac_f32_dpp v124, v125, v243 row_shr:1 row_mask:0xf bank_mask:0xf
	v_fmac_f32_dpp v124, v30, v243 row_shl:15 row_mask:0xf bank_mask:0xf
	v_fmac_f32_e32 v124, v125, v247
	v_mov_b32_e32 v74, 0
	v_mov_b32_e32 v76, 0
	v_mov_b32_e32 v77, 0
	s_cbranch_vccnz .LBB0_1192
	ds_read_b128 v[106:109], v227 offset:2064
	ds_read_b128 v[74:77], v227 offset:3088
; #define PG8_LAS __attribute__((address_space(3)))
;     __device__ __forceinline__ void operator()(f32x4 (&acc)[2][2][4][2], const Unit& u, int ui, int wr, int wc, int fr_, int fq_) const {
;     ...
;         for (int ai = 0; ai < 2; ++ai)
; #pragma unroll
;             for (int m = 0; m < 4; ++m) { const float r = rtab[ui * 256 + ai * HALF + wr * 64 + m * 16 + fr];
; #pragma unroll
;                 for (int bj = 0; bj < 2; ++bj)
; #pragma unroll
;                     for (int n = 0; n < 2; ++n) acc[ai][bj][m][n] = acc[ai][bj][m][n] * r; }
;     ...
;         for (int bj = 0; bj < 2; ++bj)
; #pragma unroll
;             for (int n = 0; n < 2; ++n) { const int ch = bj * 2816 + fbase + 4 * n;
;                 const f32x4 w0 = *(const f32x4*)(cw + ch), w1 = *(const f32x4*)(cw + 5632 + ch), w2 = *(const f32x4*)(cw + 2 * 5632 + ch), bb = *(const f32x4*)(cb + ch);
; #pragma unroll
;                 for (int ai = 0; ai < 2; ++ai) { const int kb = 2 * ai + wr;
;                     f32x4 c62 = (f32x4){0.f, 0.f, 0.f, 0.f}, c63 = c62;
;                     if (kb > 0) { c62 = *(const PG8_LAS f32x4*)(exch + (((kb - 1) * 2 + 0) * 256 + bj * HALF + 32 * wc + 8 * fq + 4 * n)); c63 = *(const PG8_LAS f32x4*)(exch + (((kb - 1) * 2 + 1) * 256 + bj * HALF + 32 * wc + 8 * fq + 4 * n)); }
; #pragma unroll
;                     for (int m = 3; m >= 0; --m) { f32x4 cur = acc[ai][bj][m][n], res;
; #pragma unroll
;                         for (int j = 0; j < 4; ++j) { const float c = cur[j]; const float pv = (m > 0) ? acc[ai][bj][m > 0 ? m - 1 : 0][n][j] : (fr == 15 ? c63[j] : c62[j]); float t1, t2;
;                             asm volatile("s_nop 1\n\tv_mov_b32_dpp %0, %3 row_ror:1 row_mask:0xf bank_mask:0xf\n\tv_mov_b32_dpp %1, %3 row_ror:2 row_mask:0xf bank_mask:0xf\n\t"
;                                          "v_mov_b32_dpp %0, %2 row_shr:1 row_mask:0xf bank_mask:0xf\n\tv_mov_b32_dpp %1, %2 row_shr:2 row_mask:0xf bank_mask:0xf"
;                                          : "=&v"(t1), "=&v"(t2) : "v"(c), "v"(pv));
;                             res[j] = bb[j] + w0[j] * t2 + w1[j] * t1 + w2[j] * c; }
;                         asm volatile("" : "+v"(res[0]), "+v"(res[1]), "+v"(res[2]), "+v"(res[3]));
;                         acc[ai][bj][m][n] = res; } }
.LBB0_1192:
	v_mov_b32_e32 v30, v192
	v_mov_b32_e32 v31, v192
	v_pk_mul_f32 v[30:31], v[68:69], v[30:31]
	v_mov_b32_e32 v189, v188
	v_pk_mul_f32 v[64:65], v[64:65], v[190:191] op_sel_hi:[1,0]
	v_mov_b32_e32 v68, v188
	v_mov_b32_e32 v69, v188
	v_pk_mul_f32 v[56:57], v[56:57], v[68:69]
	v_pk_mul_f32 v[54:55], v[54:55], v[188:189]
	v_mov_b32_e32 v191, v190
	v_pk_mul_f32 v[62:63], v[62:63], v[190:191]
	v_mov_b32_e32 v112, v248
	v_fmac_f32_dpp v112, v114, v234 row_shr:2 row_mask:0xf bank_mask:0xf
	v_fmac_f32_dpp v112, v54, v234 row_shl:14 row_mask:0xf bank_mask:0xf
	v_fmac_f32_dpp v112, v114, v240 row_shr:1 row_mask:0xf bank_mask:0xf
	v_fmac_f32_dpp v112, v54, v240 row_shl:15 row_mask:0xf bank_mask:0xf
	v_fmac_f32_e32 v112, v114, v244
	v_mov_b32_e32 v110, v249
	v_fmac_f32_dpp v110, v115, v235 row_shr:2 row_mask:0xf bank_mask:0xf
	v_fmac_f32_dpp v110, v55, v235 row_shl:14 row_mask:0xf bank_mask:0xf
	v_fmac_f32_dpp v110, v115, v241 row_shr:1 row_mask:0xf bank_mask:0xf
	v_fmac_f32_dpp v110, v55, v241 row_shl:15 row_mask:0xf bank_mask:0xf
	v_fmac_f32_e32 v110, v115, v245
	v_mov_b32_e32 v111, v250
	v_fmac_f32_dpp v111, v116, v236 row_shr:2 row_mask:0xf bank_mask:0xf
	v_fmac_f32_dpp v111, v56, v236 row_shl:14 row_mask:0xf bank_mask:0xf
	v_fmac_f32_dpp v111, v116, v242 row_shr:1 row_mask:0xf bank_mask:0xf
	v_fmac_f32_dpp v111, v56, v242 row_shl:15 row_mask:0xf bank_mask:0xf
	v_fmac_f32_e32 v111, v116, v246
	v_mov_b32_e32 v113, v251
	v_fmac_f32_dpp v113, v117, v237 row_shr:2 row_mask:0xf bank_mask:0xf
	v_fmac_f32_dpp v113, v57, v237 row_shl:14 row_mask:0xf bank_mask:0xf
	v_fmac_f32_dpp v113, v117, v243 row_shr:1 row_mask:0xf bank_mask:0xf
	v_fmac_f32_dpp v113, v57, v243 row_shl:15 row_mask:0xf bank_mask:0xf
	v_fmac_f32_e32 v113, v117, v247
	v_mov_b32_e32 v193, v192
	v_mov_b32_e32 v116, v248
	v_fmac_f32_dpp v116, v54, v234 row_shr:2 row_mask:0xf bank_mask:0xf
	v_fmac_f32_dpp v116, v62, v234 row_shl:14 row_mask:0xf bank_mask:0xf
	v_fmac_f32_dpp v116, v54, v240 row_shr:1 row_mask:0xf bank_mask:0xf
	v_fmac_f32_dpp v116, v62, v240 row_shl:15 row_mask:0xf bank_mask:0xf
	v_fmac_f32_e32 v116, v54, v244
	v_pk_mul_f32 v[66:67], v[66:67], v[192:193]
	v_mov_b32_e32 v114, v249
	v_fmac_f32_dpp v114, v55, v235 row_shr:2 row_mask:0xf bank_mask:0xf
	v_fmac_f32_dpp v114, v63, v235 row_shl:14 row_mask:0xf bank_mask:0xf
	v_fmac_f32_dpp v114, v55, v241 row_shr:1 row_mask:0xf bank_mask:0xf
	v_fmac_f32_dpp v114, v63, v241 row_shl:15 row_mask:0xf bank_mask:0xf
	v_fmac_f32_e32 v114, v55, v245
	s_movk_i32 s0, 0x2000
	v_mov_b32_e32 v115, v250
	v_fmac_f32_dpp v115, v56, v236 row_shr:2 row_mask:0xf bank_mask:0xf
	v_fmac_f32_dpp v115, v64, v236 row_shl:14 row_mask:0xf bank_mask:0xf
	v_fmac_f32_dpp v115, v56, v242 row_shr:1 row_mask:0xf bank_mask:0xf
	v_fmac_f32_dpp v115, v64, v242 row_shl:15 row_mask:0xf bank_mask:0xf
	v_fmac_f32_e32 v115, v56, v246
	v_mov_b32_e32 v117, v251
	v_fmac_f32_dpp v117, v57, v237 row_shr:2 row_mask:0xf bank_mask:0xf
	v_fmac_f32_dpp v117, v65, v237 row_shl:14 row_mask:0xf bank_mask:0xf
	v_fmac_f32_dpp v117, v57, v243 row_shr:1 row_mask:0xf bank_mask:0xf
	v_fmac_f32_dpp v117, v65, v243 row_shl:15 row_mask:0xf bank_mask:0xf
	v_fmac_f32_e32 v117, v57, v247
	s_waitcnt lgkmcnt(0)
	v_cndmask_b32_e64 v57, v106, v74, s[8:9]
	v_mov_b32_e32 v120, v248
	v_fmac_f32_dpp v120, v62, v234 row_shr:2 row_mask:0xf bank_mask:0xf
	v_fmac_f32_dpp v120, v66, v234 row_shl:14 row_mask:0xf bank_mask:0xf
	v_fmac_f32_dpp v120, v62, v240 row_shr:1 row_mask:0xf bank_mask:0xf
	v_fmac_f32_dpp v120, v66, v240 row_shl:15 row_mask:0xf bank_mask:0xf
	v_fmac_f32_e32 v120, v62, v244
	v_mov_b32_e32 v118, v249
	v_fmac_f32_dpp v118, v63, v235 row_shr:2 row_mask:0xf bank_mask:0xf
	v_fmac_f32_dpp v118, v67, v235 row_shl:14 row_mask:0xf bank_mask:0xf
	v_fmac_f32_dpp v118, v63, v241 row_shr:1 row_mask:0xf bank_mask:0xf
	v_fmac_f32_dpp v118, v67, v241 row_shl:15 row_mask:0xf bank_mask:0xf
	v_fmac_f32_e32 v118, v63, v245
	v_mov_b32_e32 v119, v250
	v_fmac_f32_dpp v119, v64, v236 row_shr:2 row_mask:0xf bank_mask:0xf
	v_fmac_f32_dpp v119, v30, v236 row_shl:14 row_mask:0xf bank_mask:0xf
	v_fmac_f32_dpp v119, v64, v242 row_shr:1 row_mask:0xf bank_mask:0xf
	v_fmac_f32_dpp v119, v30, v242 row_shl:15 row_mask:0xf bank_mask:0xf
	v_fmac_f32_e32 v119, v64, v246
	v_mov_b32_e32 v121, v251
	v_fmac_f32_dpp v121, v65, v237 row_shr:2 row_mask:0xf bank_mask:0xf
	v_fmac_f32_dpp v121, v31, v237 row_shl:14 row_mask:0xf bank_mask:0xf
	v_fmac_f32_dpp v121, v65, v243 row_shr:1 row_mask:0xf bank_mask:0xf
	v_fmac_f32_dpp v121, v31, v243 row_shl:15 row_mask:0xf bank_mask:0xf
	v_fmac_f32_e32 v121, v65, v247
	v_cndmask_b32_e64 v56, v107, v75, s[8:9]
	v_mov_b32_e32 v106, v248
	v_fmac_f32_dpp v106, v66, v234 row_shr:2 row_mask:0xf bank_mask:0xf
	v_fmac_f32_dpp v106, v57, v234 row_shl:14 row_mask:0xf bank_mask:0xf
	v_fmac_f32_dpp v106, v66, v240 row_shr:1 row_mask:0xf bank_mask:0xf
	v_fmac_f32_dpp v106, v57, v240 row_shl:15 row_mask:0xf bank_mask:0xf
	v_cndmask_b32_e64 v55, v108, v76, s[8:9]
	v_mov_b32_e32 v102, v249
	v_fmac_f32_dpp v102, v67, v235 row_shr:2 row_mask:0xf bank_mask:0xf
	v_fmac_f32_dpp v102, v56, v235 row_shl:14 row_mask:0xf bank_mask:0xf
	v_fmac_f32_dpp v102, v67, v241 row_shr:1 row_mask:0xf bank_mask:0xf
	v_fmac_f32_dpp v102, v56, v241 row_shl:15 row_mask:0xf bank_mask:0xf
	s_nop 1
	v_mov_b32_dpp v46, v55 row_ror:1 row_mask:0xf bank_mask:0xf
	v_mov_b32_dpp v47, v55 row_ror:2 row_mask:0xf bank_mask:0xf
	v_mov_b32_dpp v46, v30 row_shr:1 row_mask:0xf bank_mask:0xf
	v_mov_b32_dpp v47, v30 row_shr:2 row_mask:0xf bank_mask:0xf
	v_cndmask_b32_e64 v54, v109, v77, s[8:9]
	v_mov_b32_e32 v48, v250
	v_fma_f32 v48, v236, v47, v48
; #define PG8_LAS __attribute__((address_space(3)))
;     __device__ __forceinline__ void operator()(f32x4 (&acc)[2][2][4][2], const Unit& u, int ui, int wr, int wc, int fr_, int fq_) const {
;     ...
;         for (int bj = 0; bj < 2; ++bj)
; #pragma unroll
;             for (int n = 0; n < 2; ++n) { const int ch = bj * 2816 + fbase + 4 * n;
;                 const f32x4 w0 = *(const f32x4*)(cw + ch), w1 = *(const f32x4*)(cw + 5632 + ch), w2 = *(const f32x4*)(cw + 2 * 5632 + ch), bb = *(const f32x4*)(cb + ch);
; #pragma unroll
;                 for (int ai = 0; ai < 2; ++ai) { const int kb = 2 * ai + wr;
;                     f32x4 c62 = (f32x4){0.f, 0.f, 0.f, 0.f}, c63 = c62;
;                     if (kb > 0) { c62 = *(const PG8_LAS f32x4*)(exch + (((kb - 1) * 2 + 0) * 256 + bj * HALF + 32 * wc + 8 * fq + 4 * n)); c63 = *(const PG8_LAS f32x4*)(exch + (((kb - 1) * 2 + 1) * 256 + bj * HALF + 32 * wc + 8 * fq + 4 * n)); }
; #pragma unroll
;                     for (int m = 3; m >= 0; --m) { f32x4 cur = acc[ai][bj][m][n], res;
; #pragma unroll
;                         for (int j = 0; j < 4; ++j) { const float c = cur[j]; const float pv = (m > 0) ? acc[ai][bj][m > 0 ? m - 1 : 0][n][j] : (fr == 15 ? c63[j] : c62[j]); float t1, t2;
;                             asm volatile("s_nop 1\n\tv_mov_b32_dpp %0, %3 row_ror:1 row_mask:0xf bank_mask:0xf\n\tv_mov_b32_dpp %1, %3 row_ror:2 row_mask:0xf bank_mask:0xf\n\t"
;                                          "v_mov_b32_dpp %0, %2 row_shr:1 row_mask:0xf bank_mask:0xf\n\tv_mov_b32_dpp %1, %2 row_shr:2 row_mask:0xf bank_mask:0xf"
;                                          : "=&v"(t1), "=&v"(t2) : "v"(c), "v"(pv));
;                             res[j] = bb[j] + w0[j] * t2 + w1[j] * t1 + w2[j] * c; }
;                         asm volatile("" : "+v"(res[0]), "+v"(res[1]), "+v"(res[2]), "+v"(res[3]));
;                         acc[ai][bj][m][n] = res; } }
	v_fmac_f32_e32 v48, v242, v46
	v_fmac_f32_e32 v48, v30, v246
	s_nop 1
	v_mov_b32_dpp v30, v54 row_ror:1 row_mask:0xf bank_mask:0xf
	v_mov_b32_dpp v46, v54 row_ror:2 row_mask:0xf bank_mask:0xf
	v_mov_b32_dpp v30, v31 row_shr:1 row_mask:0xf bank_mask:0xf
	v_mov_b32_dpp v46, v31 row_shr:2 row_mask:0xf bank_mask:0xf
	v_fmac_f32_e32 v106, v66, v244
	v_mov_b32_e32 v49, v251
	v_fmac_f32_e32 v49, v237, v46
	v_fmac_f32_e32 v49, v243, v30
	v_add_co_u32_e32 v30, vcc, s0, v204
	v_fmac_f32_e32 v49, v31, v247
	s_nop 0
	v_addc_co_u32_e32 v31, vcc, 0, v205, vcc
	v_add_co_u32_e32 v46, vcc, s0, v202
	v_fmac_f32_e32 v102, v67, v245
	s_nop 0
	v_addc_co_u32_e32 v47, vcc, 0, v203, vcc
	v_add_co_u32_e32 v54, vcc, 0x2000, v200
	global_load_dwordx4 v[62:65], v[30:31], off offset:3072
	global_load_dwordx4 v[66:69], v[46:47], off offset:3072
	global_load_dwordx4 v[234:237], v[30:31], off offset:3088
	global_load_dwordx4 v[240:243], v[46:47], off offset:3088
	v_addc_co_u32_e32 v55, vcc, 0, v201, vcc
	global_load_dwordx4 v[74:77], v[54:55], off offset:3072
	global_load_dwordx4 v[244:247], v[54:55], off offset:3088
	v_add_co_u32_e32 v54, vcc, 0x2000, v198
	v_mov_b32_e32 v78, 0
	s_nop 0
	v_addc_co_u32_e32 v55, vcc, 0, v199, vcc
	global_load_dwordx4 v[248:251], v[54:55], off offset:3088
	global_load_dwordx4 v[54:57], v[54:55], off offset:3072
	s_and_b64 vcc, exec, s[10:11]
	v_mov_b32_e32 v90, 0
	v_mov_b32_e32 v91, 0
	v_mov_b32_e32 v92, 0
	v_mov_b32_e32 v93, 0
	v_mov_b32_e32 v94, 0
	v_mov_b32_e32 v95, 0
	v_mov_b32_e32 v96, 0
	v_mov_b32_e32 v97, 0
	s_cbranch_vccnz .LBB0_1194
	v_add_u32_e32 v80, s43, v228
	v_add_u32_e32 v79, s30, v228
	ds_read_b128 v[90:93], v80
	ds_read_b128 v[94:97], v79
.LBB0_1194:
	v_pk_mul_f32 v[44:45], v[44:45], v[194:195] op_sel_hi:[1,0]
	v_pk_mul_f32 v[40:41], v[40:41], v[196:197] op_sel_hi:[1,0]
	v_pk_mul_f32 v[38:39], v[38:39], v[196:197]
	v_pk_mul_f32 v[42:43], v[42:43], v[194:195]
	s_and_b64 vcc, exec, s[12:13]
	s_waitcnt vmcnt(0)
	v_mov_b32_e32 v104, v54
	v_fmac_f32_dpp v104, v98, v62 row_shr:2 row_mask:0xf bank_mask:0xf
	v_fmac_f32_dpp v104, v38, v62 row_shl:14 row_mask:0xf bank_mask:0xf
	v_fmac_f32_dpp v104, v98, v66 row_shr:1 row_mask:0xf bank_mask:0xf
	v_fmac_f32_dpp v104, v38, v66 row_shl:15 row_mask:0xf bank_mask:0xf
	v_fmac_f32_e32 v104, v98, v74
	v_mov_b32_e32 v103, v55
	v_fmac_f32_dpp v103, v99, v63 row_shr:2 row_mask:0xf bank_mask:0xf
	v_fmac_f32_dpp v103, v39, v63 row_shl:14 row_mask:0xf bank_mask:0xf
	v_fmac_f32_dpp v103, v99, v67 row_shr:1 row_mask:0xf bank_mask:0xf
	v_fmac_f32_dpp v103, v39, v67 row_shl:15 row_mask:0xf bank_mask:0xf
	v_fmac_f32_e32 v103, v99, v75
	v_mov_b32_e32 v98, v56
	v_fmac_f32_dpp v98, v100, v64 row_shr:2 row_mask:0xf bank_mask:0xf
	v_fmac_f32_dpp v98, v40, v64 row_shl:14 row_mask:0xf bank_mask:0xf
	v_fmac_f32_dpp v98, v100, v68 row_shr:1 row_mask:0xf bank_mask:0xf
	v_fmac_f32_dpp v98, v40, v68 row_shl:15 row_mask:0xf bank_mask:0xf
	v_fmac_f32_e32 v98, v100, v76
	v_mov_b32_e32 v99, v57
	v_fmac_f32_dpp v99, v101, v65 row_shr:2 row_mask:0xf bank_mask:0xf
	v_fmac_f32_dpp v99, v41, v65 row_shl:14 row_mask:0xf bank_mask:0xf
	v_fmac_f32_dpp v99, v101, v69 row_shr:1 row_mask:0xf bank_mask:0xf
	v_fmac_f32_dpp v99, v41, v69 row_shl:15 row_mask:0xf bank_mask:0xf
	v_fmac_f32_e32 v99, v101, v77
	v_mov_b32_e32 v81, 0
	v_mov_b32_e32 v107, v54
	v_fmac_f32_dpp v107, v38, v62 row_shr:2 row_mask:0xf bank_mask:0xf
	v_fmac_f32_dpp v107, v42, v62 row_shl:14 row_mask:0xf bank_mask:0xf
	v_fmac_f32_dpp v107, v38, v66 row_shr:1 row_mask:0xf bank_mask:0xf
	v_fmac_f32_dpp v107, v42, v66 row_shl:15 row_mask:0xf bank_mask:0xf
	v_fmac_f32_e32 v107, v38, v74
	v_mov_b32_e32 v80, 0
	v_mov_b32_e32 v105, v55
	v_fmac_f32_dpp v105, v39, v63 row_shr:2 row_mask:0xf bank_mask:0xf
	v_fmac_f32_dpp v105, v43, v63 row_shl:14 row_mask:0xf bank_mask:0xf
	v_fmac_f32_dpp v105, v39, v67 row_shr:1 row_mask:0xf bank_mask:0xf
	v_fmac_f32_dpp v105, v43, v67 row_shl:15 row_mask:0xf bank_mask:0xf
	v_fmac_f32_e32 v105, v39, v75
	v_mov_b32_e32 v79, 0
	v_mov_b32_e32 v100, v56
	v_fmac_f32_dpp v100, v40, v64 row_shr:2 row_mask:0xf bank_mask:0xf
	v_fmac_f32_dpp v100, v44, v64 row_shl:14 row_mask:0xf bank_mask:0xf
	v_fmac_f32_dpp v100, v40, v68 row_shr:1 row_mask:0xf bank_mask:0xf
	v_fmac_f32_dpp v100, v44, v68 row_shl:15 row_mask:0xf bank_mask:0xf
	v_fmac_f32_e32 v100, v40, v76
	v_mov_b32_e32 v101, v57
	v_fmac_f32_dpp v101, v41, v65 row_shr:2 row_mask:0xf bank_mask:0xf
	v_fmac_f32_dpp v101, v45, v65 row_shl:14 row_mask:0xf bank_mask:0xf
	v_fmac_f32_dpp v101, v41, v69 row_shr:1 row_mask:0xf bank_mask:0xf
	v_fmac_f32_dpp v101, v45, v69 row_shl:15 row_mask:0xf bank_mask:0xf
	v_fmac_f32_e32 v101, v41, v77
	s_waitcnt lgkmcnt(0)
; #define PG8_LAS __attribute__((address_space(3)))
;     __device__ __forceinline__ void operator()(f32x4 (&acc)[2][2][4][2], const Unit& u, int ui, int wr, int wc, int fr_, int fq_) const {
;     ...
;         for (int ai = 0; ai < 2; ++ai)
; #pragma unroll
;             for (int m = 0; m < 4; ++m) { const float r = rtab[ui * 256 + ai * HALF + wr * 64 + m * 16 + fr];
; #pragma unroll
;                 for (int bj = 0; bj < 2; ++bj)
; #pragma unroll
;                     for (int n = 0; n < 2; ++n) acc[ai][bj][m][n] = acc[ai][bj][m][n] * r; }
;     ...
;         for (int bj = 0; bj < 2; ++bj)
; #pragma unroll
;             for (int n = 0; n < 2; ++n) { const int ch = bj * 2816 + fbase + 4 * n;
;                 const f32x4 w0 = *(const f32x4*)(cw + ch), w1 = *(const f32x4*)(cw + 5632 + ch), w2 = *(const f32x4*)(cw + 2 * 5632 + ch), bb = *(const f32x4*)(cb + ch);
; #pragma unroll
;                 for (int ai = 0; ai < 2; ++ai) { const int kb = 2 * ai + wr;
;                     f32x4 c62 = (f32x4){0.f, 0.f, 0.f, 0.f}, c63 = c62;
;                     if (kb > 0) { c62 = *(const PG8_LAS f32x4*)(exch + (((kb - 1) * 2 + 0) * 256 + bj * HALF + 32 * wc + 8 * fq + 4 * n)); c63 = *(const PG8_LAS f32x4*)(exch + (((kb - 1) * 2 + 1) * 256 + bj * HALF + 32 * wc + 8 * fq + 4 * n)); }
; #pragma unroll
;                     for (int m = 3; m >= 0; --m) { f32x4 cur = acc[ai][bj][m][n], res;
; #pragma unroll
;                         for (int j = 0; j < 4; ++j) { const float c = cur[j]; const float pv = (m > 0) ? acc[ai][bj][m > 0 ? m - 1 : 0][n][j] : (fr == 15 ? c63[j] : c62[j]); float t1, t2;
;                             asm volatile("s_nop 1\n\tv_mov_b32_dpp %0, %3 row_ror:1 row_mask:0xf bank_mask:0xf\n\tv_mov_b32_dpp %1, %3 row_ror:2 row_mask:0xf bank_mask:0xf\n\t"
;                                          "v_mov_b32_dpp %0, %2 row_shr:1 row_mask:0xf bank_mask:0xf\n\tv_mov_b32_dpp %1, %2 row_shr:2 row_mask:0xf bank_mask:0xf"
;                                          : "=&v"(t1), "=&v"(t2) : "v"(c), "v"(pv));
;                             res[j] = bb[j] + w0[j] * t2 + w1[j] * t1 + w2[j] * c; }
;                         asm volatile("" : "+v"(res[0]), "+v"(res[1]), "+v"(res[2]), "+v"(res[3]));
;                         acc[ai][bj][m][n] = res; } }
	v_cndmask_b32_e64 v41, v90, v94, s[8:9]
	v_mov_b32_e32 v127, v54
	v_fmac_f32_dpp v127, v42, v62 row_shr:2 row_mask:0xf bank_mask:0xf
	v_fmac_f32_dpp v127, v86, v62 row_shl:14 row_mask:0xf bank_mask:0xf
	v_fmac_f32_dpp v127, v42, v66 row_shr:1 row_mask:0xf bank_mask:0xf
	v_fmac_f32_dpp v127, v86, v66 row_shl:15 row_mask:0xf bank_mask:0xf
	v_fmac_f32_e32 v127, v42, v74
	v_mov_b32_e32 v125, v55
	v_fmac_f32_dpp v125, v43, v63 row_shr:2 row_mask:0xf bank_mask:0xf
	v_fmac_f32_dpp v125, v87, v63 row_shl:14 row_mask:0xf bank_mask:0xf
	v_fmac_f32_dpp v125, v43, v67 row_shr:1 row_mask:0xf bank_mask:0xf
	v_fmac_f32_dpp v125, v87, v67 row_shl:15 row_mask:0xf bank_mask:0xf
	v_fmac_f32_e32 v125, v43, v75
	v_mov_b32_e32 v108, v56
	v_fmac_f32_dpp v108, v44, v64 row_shr:2 row_mask:0xf bank_mask:0xf
	v_fmac_f32_dpp v108, v88, v64 row_shl:14 row_mask:0xf bank_mask:0xf
	v_fmac_f32_dpp v108, v44, v68 row_shr:1 row_mask:0xf bank_mask:0xf
	v_fmac_f32_dpp v108, v88, v68 row_shl:15 row_mask:0xf bank_mask:0xf
	v_fmac_f32_e32 v108, v44, v76
	v_mov_b32_e32 v109, v57
	v_fmac_f32_dpp v109, v45, v65 row_shr:2 row_mask:0xf bank_mask:0xf
	v_fmac_f32_dpp v109, v89, v65 row_shl:14 row_mask:0xf bank_mask:0xf
	v_fmac_f32_dpp v109, v45, v69 row_shr:1 row_mask:0xf bank_mask:0xf
	v_fmac_f32_dpp v109, v89, v69 row_shl:15 row_mask:0xf bank_mask:0xf
	v_fmac_f32_e32 v109, v45, v77
	v_cndmask_b32_e64 v38, v93, v97, s[8:9]
	v_cndmask_b32_e64 v39, v92, v96, s[8:9]
	v_mov_b32_e32 v97, v54
	v_fmac_f32_dpp v97, v86, v62 row_shr:2 row_mask:0xf bank_mask:0xf
	v_fmac_f32_dpp v97, v41, v62 row_shl:14 row_mask:0xf bank_mask:0xf
	v_fmac_f32_dpp v97, v86, v66 row_shr:1 row_mask:0xf bank_mask:0xf
	v_fmac_f32_dpp v97, v41, v66 row_shl:15 row_mask:0xf bank_mask:0xf
	v_cndmask_b32_e64 v40, v91, v95, s[8:9]
	v_fmac_f32_e32 v97, v86, v74
	v_mov_b32_e32 v96, v55
	v_fmac_f32_dpp v96, v87, v63 row_shr:2 row_mask:0xf bank_mask:0xf
	v_fmac_f32_dpp v96, v40, v63 row_shl:14 row_mask:0xf bank_mask:0xf
	v_fmac_f32_dpp v96, v87, v67 row_shr:1 row_mask:0xf bank_mask:0xf
	v_fmac_f32_dpp v96, v40, v67 row_shl:15 row_mask:0xf bank_mask:0xf
	v_fmac_f32_e32 v96, v87, v75
	v_mov_b32_e32 v95, v56
	v_fmac_f32_dpp v95, v88, v64 row_shr:2 row_mask:0xf bank_mask:0xf
	v_fmac_f32_dpp v95, v39, v64 row_shl:14 row_mask:0xf bank_mask:0xf
	v_fmac_f32_dpp v95, v88, v68 row_shr:1 row_mask:0xf bank_mask:0xf
	v_fmac_f32_dpp v95, v39, v68 row_shl:15 row_mask:0xf bank_mask:0xf
	v_fmac_f32_e32 v95, v88, v76
	v_mov_b32_e32 v94, v57
	v_fmac_f32_dpp v94, v89, v65 row_shr:2 row_mask:0xf bank_mask:0xf
	v_fmac_f32_dpp v94, v38, v65 row_shl:14 row_mask:0xf bank_mask:0xf
	v_fmac_f32_dpp v94, v89, v69 row_shr:1 row_mask:0xf bank_mask:0xf
	v_fmac_f32_dpp v94, v38, v69 row_shl:15 row_mask:0xf bank_mask:0xf
	v_fmac_f32_e32 v94, v89, v77
	v_mov_b32_e32 v38, 0
	v_mov_b32_e32 v39, 0
	v_mov_b32_e32 v40, 0
	v_mov_b32_e32 v41, 0
	s_cbranch_vccnz .LBB0_1196
	ds_read_b128 v[78:81], v227 offset:2560
	ds_read_b128 v[38:41], v227 offset:3584
.LBB0_1196:
	v_pk_mul_f32 v[36:37], v[36:37], v[192:193] op_sel_hi:[1,0]
	v_pk_mul_f32 v[28:29], v[28:29], v[190:191] op_sel_hi:[1,0]
	v_pk_mul_f32 v[24:25], v[24:25], v[188:189] op_sel_hi:[1,0]
	v_pk_mul_f32 v[22:23], v[22:23], v[188:189]
	v_pk_mul_f32 v[26:27], v[26:27], v[190:191]
	v_pk_mul_f32 v[34:35], v[34:35], v[192:193]
	v_mov_b32_e32 v87, v54
	v_fmac_f32_dpp v87, v82, v62 row_shr:2 row_mask:0xf bank_mask:0xf
	v_fmac_f32_dpp v87, v22, v62 row_shl:14 row_mask:0xf bank_mask:0xf
	v_fmac_f32_dpp v87, v82, v66 row_shr:1 row_mask:0xf bank_mask:0xf
	v_fmac_f32_dpp v87, v22, v66 row_shl:15 row_mask:0xf bank_mask:0xf
	v_fmac_f32_e32 v87, v82, v74
	v_mov_b32_e32 v86, v55
	v_fmac_f32_dpp v86, v83, v63 row_shr:2 row_mask:0xf bank_mask:0xf
	v_fmac_f32_dpp v86, v23, v63 row_shl:14 row_mask:0xf bank_mask:0xf
	v_fmac_f32_dpp v86, v83, v67 row_shr:1 row_mask:0xf bank_mask:0xf
	v_fmac_f32_dpp v86, v23, v67 row_shl:15 row_mask:0xf bank_mask:0xf
	v_fmac_f32_e32 v86, v83, v75
	v_mov_b32_e32 v82, v56
	v_fmac_f32_dpp v82, v84, v64 row_shr:2 row_mask:0xf bank_mask:0xf
	v_fmac_f32_dpp v82, v24, v64 row_shl:14 row_mask:0xf bank_mask:0xf
	v_fmac_f32_dpp v82, v84, v68 row_shr:1 row_mask:0xf bank_mask:0xf
	v_fmac_f32_dpp v82, v24, v68 row_shl:15 row_mask:0xf bank_mask:0xf
	v_fmac_f32_e32 v82, v84, v76
	v_mov_b32_e32 v83, v57
	v_fmac_f32_dpp v83, v85, v65 row_shr:2 row_mask:0xf bank_mask:0xf
	v_fmac_f32_dpp v83, v25, v65 row_shl:14 row_mask:0xf bank_mask:0xf
	v_fmac_f32_dpp v83, v85, v69 row_shr:1 row_mask:0xf bank_mask:0xf
	v_fmac_f32_dpp v83, v25, v69 row_shl:15 row_mask:0xf bank_mask:0xf
	v_fmac_f32_e32 v83, v85, v77
	v_mov_b32_e32 v44, 0
	v_mov_b32_e32 v89, v54
	v_fmac_f32_dpp v89, v22, v62 row_shr:2 row_mask:0xf bank_mask:0xf
	v_fmac_f32_dpp v89, v26, v62 row_shl:14 row_mask:0xf bank_mask:0xf
	v_fmac_f32_dpp v89, v22, v66 row_shr:1 row_mask:0xf bank_mask:0xf
	v_fmac_f32_dpp v89, v26, v66 row_shl:15 row_mask:0xf bank_mask:0xf
	v_fmac_f32_e32 v89, v22, v74
	v_mov_b32_e32 v45, 0
	v_mov_b32_e32 v88, v55
	v_fmac_f32_dpp v88, v23, v63 row_shr:2 row_mask:0xf bank_mask:0xf
	v_fmac_f32_dpp v88, v27, v63 row_shl:14 row_mask:0xf bank_mask:0xf
	v_fmac_f32_dpp v88, v23, v67 row_shr:1 row_mask:0xf bank_mask:0xf
	v_fmac_f32_dpp v88, v27, v67 row_shl:15 row_mask:0xf bank_mask:0xf
	v_fmac_f32_e32 v88, v23, v75
	v_mov_b32_e32 v42, 0
	v_mov_b32_e32 v84, v56
	v_fmac_f32_dpp v84, v24, v64 row_shr:2 row_mask:0xf bank_mask:0xf
	v_fmac_f32_dpp v84, v28, v64 row_shl:14 row_mask:0xf bank_mask:0xf
	v_fmac_f32_dpp v84, v24, v68 row_shr:1 row_mask:0xf bank_mask:0xf
	v_fmac_f32_dpp v84, v28, v68 row_shl:15 row_mask:0xf bank_mask:0xf
	v_fmac_f32_e32 v84, v24, v76
	v_mov_b32_e32 v85, v57
	v_fmac_f32_dpp v85, v25, v65 row_shr:2 row_mask:0xf bank_mask:0xf
	v_fmac_f32_dpp v85, v29, v65 row_shl:14 row_mask:0xf bank_mask:0xf
	v_fmac_f32_dpp v85, v25, v69 row_shr:1 row_mask:0xf bank_mask:0xf
	v_fmac_f32_dpp v85, v29, v69 row_shl:15 row_mask:0xf bank_mask:0xf
	v_fmac_f32_e32 v85, v25, v77
	s_waitcnt lgkmcnt(0)
; #define PG8_LAS __attribute__((address_space(3)))
;     __device__ __forceinline__ void operator()(f32x4 (&acc)[2][2][4][2], const Unit& u, int ui, int wr, int wc, int fr_, int fq_) const {
;     ...
;         for (int ai = 0; ai < 2; ++ai)
; #pragma unroll
;             for (int m = 0; m < 4; ++m) { const float r = rtab[ui * 256 + ai * HALF + wr * 64 + m * 16 + fr];
; #pragma unroll
;                 for (int bj = 0; bj < 2; ++bj)
; #pragma unroll
;                     for (int n = 0; n < 2; ++n) acc[ai][bj][m][n] = acc[ai][bj][m][n] * r; }
;     ...
;         for (int bj = 0; bj < 2; ++bj)
; #pragma unroll
;             for (int n = 0; n < 2; ++n) { const int ch = bj * 2816 + fbase + 4 * n;
;                 const f32x4 w0 = *(const f32x4*)(cw + ch), w1 = *(const f32x4*)(cw + 5632 + ch), w2 = *(const f32x4*)(cw + 2 * 5632 + ch), bb = *(const f32x4*)(cb + ch);
; #pragma unroll
;                 for (int ai = 0; ai < 2; ++ai) { const int kb = 2 * ai + wr;
;                     f32x4 c62 = (f32x4){0.f, 0.f, 0.f, 0.f}, c63 = c62;
;                     if (kb > 0) { c62 = *(const PG8_LAS f32x4*)(exch + (((kb - 1) * 2 + 0) * 256 + bj * HALF + 32 * wc + 8 * fq + 4 * n)); c63 = *(const PG8_LAS f32x4*)(exch + (((kb - 1) * 2 + 1) * 256 + bj * HALF + 32 * wc + 8 * fq + 4 * n)); }
; #pragma unroll
;                     for (int m = 3; m >= 0; --m) { f32x4 cur = acc[ai][bj][m][n], res;
; #pragma unroll
;                         for (int j = 0; j < 4; ++j) { const float c = cur[j]; const float pv = (m > 0) ? acc[ai][bj][m > 0 ? m - 1 : 0][n][j] : (fr == 15 ? c63[j] : c62[j]); float t1, t2;
;                             asm volatile("s_nop 1\n\tv_mov_b32_dpp %0, %3 row_ror:1 row_mask:0xf bank_mask:0xf\n\tv_mov_b32_dpp %1, %3 row_ror:2 row_mask:0xf bank_mask:0xf\n\t"
;                                          "v_mov_b32_dpp %0, %2 row_shr:1 row_mask:0xf bank_mask:0xf\n\tv_mov_b32_dpp %1, %2 row_shr:2 row_mask:0xf bank_mask:0xf"
;                                          : "=&v"(t1), "=&v"(t2) : "v"(c), "v"(pv));
;                             res[j] = bb[j] + w0[j] * t2 + w1[j] * t1 + w2[j] * c; }
;                         asm volatile("" : "+v"(res[0]), "+v"(res[1]), "+v"(res[2]), "+v"(res[3]));
;                         acc[ai][bj][m][n] = res; } }
	v_cndmask_b32_e64 v25, v78, v38, s[8:9]
	v_mov_b32_e32 v93, v54
	v_fmac_f32_dpp v93, v26, v62 row_shr:2 row_mask:0xf bank_mask:0xf
	v_fmac_f32_dpp v93, v34, v62 row_shl:14 row_mask:0xf bank_mask:0xf
	v_fmac_f32_dpp v93, v26, v66 row_shr:1 row_mask:0xf bank_mask:0xf
	v_fmac_f32_dpp v93, v34, v66 row_shl:15 row_mask:0xf bank_mask:0xf
	v_fmac_f32_e32 v93, v26, v74
	v_mov_b32_e32 v92, v55
	v_fmac_f32_dpp v92, v27, v63 row_shr:2 row_mask:0xf bank_mask:0xf
	v_fmac_f32_dpp v92, v35, v63 row_shl:14 row_mask:0xf bank_mask:0xf
	v_fmac_f32_dpp v92, v27, v67 row_shr:1 row_mask:0xf bank_mask:0xf
	v_fmac_f32_dpp v92, v35, v67 row_shl:15 row_mask:0xf bank_mask:0xf
	v_fmac_f32_e32 v92, v27, v75
	v_mov_b32_e32 v90, v56
	v_fmac_f32_dpp v90, v28, v64 row_shr:2 row_mask:0xf bank_mask:0xf
	v_fmac_f32_dpp v90, v36, v64 row_shl:14 row_mask:0xf bank_mask:0xf
	v_fmac_f32_dpp v90, v28, v68 row_shr:1 row_mask:0xf bank_mask:0xf
	v_fmac_f32_dpp v90, v36, v68 row_shl:15 row_mask:0xf bank_mask:0xf
	v_fmac_f32_e32 v90, v28, v76
	v_mov_b32_e32 v91, v57
	v_fmac_f32_dpp v91, v29, v65 row_shr:2 row_mask:0xf bank_mask:0xf
	v_fmac_f32_dpp v91, v37, v65 row_shl:14 row_mask:0xf bank_mask:0xf
	v_fmac_f32_dpp v91, v29, v69 row_shr:1 row_mask:0xf bank_mask:0xf
	v_fmac_f32_dpp v91, v37, v69 row_shl:15 row_mask:0xf bank_mask:0xf
	v_fmac_f32_e32 v91, v29, v77
	v_cndmask_b32_e64 v24, v79, v39, s[8:9]
	v_mov_b32_e32 v78, v54
	v_fmac_f32_dpp v78, v34, v62 row_shr:2 row_mask:0xf bank_mask:0xf
	v_fmac_f32_dpp v78, v25, v62 row_shl:14 row_mask:0xf bank_mask:0xf
	v_fmac_f32_dpp v78, v34, v66 row_shr:1 row_mask:0xf bank_mask:0xf
	v_fmac_f32_dpp v78, v25, v66 row_shl:15 row_mask:0xf bank_mask:0xf
	s_nop 1
	v_mov_b32_dpp v25, v24 row_ror:1 row_mask:0xf bank_mask:0xf
	v_mov_b32_dpp v26, v24 row_ror:2 row_mask:0xf bank_mask:0xf
	v_mov_b32_dpp v25, v35 row_shr:1 row_mask:0xf bank_mask:0xf
	v_mov_b32_dpp v26, v35 row_shr:2 row_mask:0xf bank_mask:0xf
	v_cndmask_b32_e64 v23, v80, v40, s[8:9]
	v_fma_f32 v55, v63, v26, v55
	v_fmac_f32_e32 v55, v67, v25
	v_cndmask_b32_e64 v22, v81, v41, s[8:9]
	v_mov_b32_e32 v54, v56
	v_fmac_f32_dpp v54, v36, v64 row_shr:2 row_mask:0xf bank_mask:0xf
	v_fmac_f32_dpp v54, v23, v64 row_shl:14 row_mask:0xf bank_mask:0xf
	v_fmac_f32_dpp v54, v36, v68 row_shr:1 row_mask:0xf bank_mask:0xf
	v_fmac_f32_dpp v54, v23, v68 row_shl:15 row_mask:0xf bank_mask:0xf
	s_nop 1
	v_mov_b32_dpp v23, v22 row_ror:1 row_mask:0xf bank_mask:0xf
	v_mov_b32_dpp v24, v22 row_ror:2 row_mask:0xf bank_mask:0xf
	v_mov_b32_dpp v23, v37 row_shr:1 row_mask:0xf bank_mask:0xf
	v_mov_b32_dpp v24, v37 row_shr:2 row_mask:0xf bank_mask:0xf
	v_fmac_f32_e32 v78, v34, v74
	v_fmac_f32_e32 v57, v65, v24
	v_fmac_f32_e32 v57, v69, v23
	v_fmac_f32_e32 v55, v35, v75
	v_fmac_f32_e32 v54, v36, v76
	v_fmac_f32_e32 v57, v37, v77
	s_waitcnt vmcnt(0)
	v_mov_b32_e32 v26, v234
	v_mov_b32_e32 v27, v235
	v_mov_b32_e32 v28, v236
	v_mov_b32_e32 v29, v237
	v_mov_b32_e32 v22, v240
	v_mov_b32_e32 v23, v241
	v_mov_b32_e32 v24, v242
	v_mov_b32_e32 v25, v243
	v_add_co_u32_e32 v30, vcc, 0x2000, v200
	v_mov_b32_e32 v46, 0
	s_nop 0
	v_addc_co_u32_e32 v31, vcc, 0, v201, vcc
	v_mov_b32_e32 v34, v244
	v_mov_b32_e32 v35, v245
	v_mov_b32_e32 v36, v246
	v_mov_b32_e32 v37, v247
	v_add_co_u32_e32 v30, vcc, 0x2000, v198
	v_mov_b32_e32 v47, 0
	s_nop 0
	v_addc_co_u32_e32 v31, vcc, 0, v199, vcc
	v_mov_b32_e32 v38, v248
	v_mov_b32_e32 v39, v249
	v_mov_b32_e32 v40, v250
	v_mov_b32_e32 v41, v251
	s_and_b64 vcc, exec, s[10:11]
	v_mov_b32_e32 v62, 0
	v_mov_b32_e32 v63, 0
	v_mov_b32_e32 v64, 0
	v_mov_b32_e32 v65, 0
	s_cbranch_vccnz .LBB0_1198
	v_add_u32_e32 v31, 0xfffffa10, v227
	v_add_u32_e32 v30, 0xfffffe10, v227
	ds_read_b128 v[44:47], v31
	ds_read_b128 v[62:65], v30
.LBB0_1198:
	v_pk_mul_f32 v[76:77], v[18:19], v[194:195]
	v_pk_mul_f32 v[74:75], v[20:21], v[194:195] op_sel_hi:[1,0]
	v_pk_mul_f32 v[16:17], v[16:17], v[196:197] op_sel_hi:[1,0]
	v_pk_mul_f32 v[14:15], v[14:15], v[196:197]
	s_and_b64 vcc, exec, s[12:13]
	s_waitcnt vmcnt(0)
	v_mov_b32_e32 v20, v38
	v_fmac_f32_dpp v20, v70, v26 row_shr:2 row_mask:0xf bank_mask:0xf
	v_fmac_f32_dpp v20, v14, v26 row_shl:14 row_mask:0xf bank_mask:0xf
	v_fmac_f32_dpp v20, v70, v22 row_shr:1 row_mask:0xf bank_mask:0xf
	v_fmac_f32_dpp v20, v14, v22 row_shl:15 row_mask:0xf bank_mask:0xf
	v_fmac_f32_e32 v20, v70, v34
	v_mov_b32_e32 v18, v39
	v_fmac_f32_dpp v18, v71, v27 row_shr:2 row_mask:0xf bank_mask:0xf
	v_fmac_f32_dpp v18, v15, v27 row_shl:14 row_mask:0xf bank_mask:0xf
	v_fmac_f32_dpp v18, v71, v23 row_shr:1 row_mask:0xf bank_mask:0xf
	v_fmac_f32_dpp v18, v15, v23 row_shl:15 row_mask:0xf bank_mask:0xf
	v_fmac_f32_e32 v18, v71, v35
	v_mov_b32_e32 v19, v40
	v_fmac_f32_dpp v19, v72, v28 row_shr:2 row_mask:0xf bank_mask:0xf
	v_fmac_f32_dpp v19, v16, v28 row_shl:14 row_mask:0xf bank_mask:0xf
	v_fmac_f32_dpp v19, v72, v24 row_shr:1 row_mask:0xf bank_mask:0xf
	v_fmac_f32_dpp v19, v16, v24 row_shl:15 row_mask:0xf bank_mask:0xf
	v_fmac_f32_e32 v19, v72, v36
	v_mov_b32_e32 v21, v41
	v_fmac_f32_dpp v21, v73, v29 row_shr:2 row_mask:0xf bank_mask:0xf
	v_fmac_f32_dpp v21, v17, v29 row_shl:14 row_mask:0xf bank_mask:0xf
	v_fmac_f32_dpp v21, v73, v25 row_shr:1 row_mask:0xf bank_mask:0xf
	v_fmac_f32_dpp v21, v17, v25 row_shl:15 row_mask:0xf bank_mask:0xf
	v_fmac_f32_e32 v21, v73, v37
	s_nop 0
	v_mov_b32_e32 v56, v38
	v_fmac_f32_dpp v56, v14, v26 row_shr:2 row_mask:0xf bank_mask:0xf
	v_fmac_f32_dpp v56, v76, v26 row_shl:14 row_mask:0xf bank_mask:0xf
	v_fmac_f32_dpp v56, v14, v22 row_shr:1 row_mask:0xf bank_mask:0xf
	v_fmac_f32_dpp v56, v76, v22 row_shl:15 row_mask:0xf bank_mask:0xf
	v_fmac_f32_e32 v56, v14, v34
	s_nop 0
	v_mov_b32_e32 v30, v39
	v_fmac_f32_dpp v30, v15, v27 row_shr:2 row_mask:0xf bank_mask:0xf
	v_fmac_f32_dpp v30, v77, v27 row_shl:14 row_mask:0xf bank_mask:0xf
	v_fmac_f32_dpp v30, v15, v23 row_shr:1 row_mask:0xf bank_mask:0xf
	v_fmac_f32_dpp v30, v77, v23 row_shl:15 row_mask:0xf bank_mask:0xf
	v_fmac_f32_e32 v30, v15, v35
	s_nop 0
	v_mov_b32_e32 v31, v40
	v_fmac_f32_dpp v31, v16, v28 row_shr:2 row_mask:0xf bank_mask:0xf
	v_fmac_f32_dpp v31, v74, v28 row_shl:14 row_mask:0xf bank_mask:0xf
	v_fmac_f32_dpp v31, v16, v24 row_shr:1 row_mask:0xf bank_mask:0xf
	v_fmac_f32_dpp v31, v74, v24 row_shl:15 row_mask:0xf bank_mask:0xf
	v_fmac_f32_e32 v31, v16, v36
	v_mov_b32_e32 v66, v41
	v_fmac_f32_dpp v66, v17, v29 row_shr:2 row_mask:0xf bank_mask:0xf
	v_fmac_f32_dpp v66, v75, v29 row_shl:14 row_mask:0xf bank_mask:0xf
	v_fmac_f32_dpp v66, v17, v25 row_shr:1 row_mask:0xf bank_mask:0xf
	v_fmac_f32_dpp v66, v75, v25 row_shl:15 row_mask:0xf bank_mask:0xf
	v_fmac_f32_e32 v66, v17, v37
	s_waitcnt lgkmcnt(0)
; #define PG8_LAS __attribute__((address_space(3)))
;     __device__ __forceinline__ void operator()(f32x4 (&acc)[2][2][4][2], const Unit& u, int ui, int wr, int wc, int fr_, int fq_) const {
;     ...
;         for (int ai = 0; ai < 2; ++ai)
; #pragma unroll
;             for (int m = 0; m < 4; ++m) { const float r = rtab[ui * 256 + ai * HALF + wr * 64 + m * 16 + fr];
; #pragma unroll
;                 for (int bj = 0; bj < 2; ++bj)
; #pragma unroll
;                     for (int n = 0; n < 2; ++n) acc[ai][bj][m][n] = acc[ai][bj][m][n] * r; }
;     ...
;         for (int bj = 0; bj < 2; ++bj)
; #pragma unroll
;             for (int n = 0; n < 2; ++n) { const int ch = bj * 2816 + fbase + 4 * n;
;                 const f32x4 w0 = *(const f32x4*)(cw + ch), w1 = *(const f32x4*)(cw + 5632 + ch), w2 = *(const f32x4*)(cw + 2 * 5632 + ch), bb = *(const f32x4*)(cb + ch);
; #pragma unroll
;                 for (int ai = 0; ai < 2; ++ai) { const int kb = 2 * ai + wr;
;                     f32x4 c62 = (f32x4){0.f, 0.f, 0.f, 0.f}, c63 = c62;
;                     if (kb > 0) { c62 = *(const PG8_LAS f32x4*)(exch + (((kb - 1) * 2 + 0) * 256 + bj * HALF + 32 * wc + 8 * fq + 4 * n)); c63 = *(const PG8_LAS f32x4*)(exch + (((kb - 1) * 2 + 1) * 256 + bj * HALF + 32 * wc + 8 * fq + 4 * n)); }
; #pragma unroll
;                     for (int m = 3; m >= 0; --m) { f32x4 cur = acc[ai][bj][m][n], res;
; #pragma unroll
;                         for (int j = 0; j < 4; ++j) { const float c = cur[j]; const float pv = (m > 0) ? acc[ai][bj][m > 0 ? m - 1 : 0][n][j] : (fr == 15 ? c63[j] : c62[j]); float t1, t2;
;                             asm volatile("s_nop 1\n\tv_mov_b32_dpp %0, %3 row_ror:1 row_mask:0xf bank_mask:0xf\n\tv_mov_b32_dpp %1, %3 row_ror:2 row_mask:0xf bank_mask:0xf\n\t"
;                                          "v_mov_b32_dpp %0, %2 row_shr:1 row_mask:0xf bank_mask:0xf\n\tv_mov_b32_dpp %1, %2 row_shr:2 row_mask:0xf bank_mask:0xf"
;                                          : "=&v"(t1), "=&v"(t2) : "v"(c), "v"(pv));
;                             res[j] = bb[j] + w0[j] * t2 + w1[j] * t1 + w2[j] * c; }
;                         asm volatile("" : "+v"(res[0]), "+v"(res[1]), "+v"(res[2]), "+v"(res[3]));
;                         acc[ai][bj][m][n] = res; } }
	v_cndmask_b32_e64 v17, v44, v62, s[8:9]
	v_mov_b32_e32 v69, v38
	v_fmac_f32_dpp v69, v76, v26 row_shr:2 row_mask:0xf bank_mask:0xf
	v_fmac_f32_dpp v69, v58, v26 row_shl:14 row_mask:0xf bank_mask:0xf
	v_fmac_f32_dpp v69, v76, v22 row_shr:1 row_mask:0xf bank_mask:0xf
	v_fmac_f32_dpp v69, v58, v22 row_shl:15 row_mask:0xf bank_mask:0xf
	v_fmac_f32_e32 v69, v76, v34
	v_mov_b32_e32 v67, v39
	v_fmac_f32_dpp v67, v77, v27 row_shr:2 row_mask:0xf bank_mask:0xf
	v_fmac_f32_dpp v67, v59, v27 row_shl:14 row_mask:0xf bank_mask:0xf
	v_fmac_f32_dpp v67, v77, v23 row_shr:1 row_mask:0xf bank_mask:0xf
	v_fmac_f32_dpp v67, v59, v23 row_shl:15 row_mask:0xf bank_mask:0xf
	v_fmac_f32_e32 v67, v77, v35
	v_mov_b32_e32 v68, v40
	v_fmac_f32_dpp v68, v74, v28 row_shr:2 row_mask:0xf bank_mask:0xf
	v_fmac_f32_dpp v68, v60, v28 row_shl:14 row_mask:0xf bank_mask:0xf
	v_fmac_f32_dpp v68, v74, v24 row_shr:1 row_mask:0xf bank_mask:0xf
	v_fmac_f32_dpp v68, v60, v24 row_shl:15 row_mask:0xf bank_mask:0xf
	v_fmac_f32_e32 v68, v74, v36
	v_mov_b32_e32 v70, v41
	v_fmac_f32_dpp v70, v75, v29 row_shr:2 row_mask:0xf bank_mask:0xf
	v_fmac_f32_dpp v70, v61, v29 row_shl:14 row_mask:0xf bank_mask:0xf
	v_fmac_f32_dpp v70, v75, v25 row_shr:1 row_mask:0xf bank_mask:0xf
	v_fmac_f32_dpp v70, v61, v25 row_shl:15 row_mask:0xf bank_mask:0xf
	v_fmac_f32_e32 v70, v75, v37
	v_cndmask_b32_e64 v16, v45, v63, s[8:9]
	v_mov_b32_e32 v62, v38
	v_fmac_f32_dpp v62, v58, v26 row_shr:2 row_mask:0xf bank_mask:0xf
	v_fmac_f32_dpp v62, v17, v26 row_shl:14 row_mask:0xf bank_mask:0xf
	v_fmac_f32_dpp v62, v58, v22 row_shr:1 row_mask:0xf bank_mask:0xf
	v_fmac_f32_dpp v62, v17, v22 row_shl:15 row_mask:0xf bank_mask:0xf
	v_fmac_f32_e32 v62, v58, v34
	v_cndmask_b32_e64 v15, v46, v64, s[8:9]
	v_mov_b32_e32 v58, v39
	v_fmac_f32_dpp v58, v59, v27 row_shr:2 row_mask:0xf bank_mask:0xf
	v_fmac_f32_dpp v58, v16, v27 row_shl:14 row_mask:0xf bank_mask:0xf
	v_fmac_f32_dpp v58, v59, v23 row_shr:1 row_mask:0xf bank_mask:0xf
	v_fmac_f32_dpp v58, v16, v23 row_shl:15 row_mask:0xf bank_mask:0xf
	v_fmac_f32_e32 v58, v59, v35
	v_cndmask_b32_e64 v14, v47, v65, s[8:9]
	v_mov_b32_e32 v59, v40
	v_fmac_f32_dpp v59, v60, v28 row_shr:2 row_mask:0xf bank_mask:0xf
	v_fmac_f32_dpp v59, v15, v28 row_shl:14 row_mask:0xf bank_mask:0xf
	v_fmac_f32_dpp v59, v60, v24 row_shr:1 row_mask:0xf bank_mask:0xf
	v_fmac_f32_dpp v59, v15, v24 row_shl:15 row_mask:0xf bank_mask:0xf
	v_fmac_f32_e32 v59, v60, v36
	v_mov_b32_e32 v43, 0
	v_mov_b32_e32 v60, v41
	v_fmac_f32_dpp v60, v61, v29 row_shr:2 row_mask:0xf bank_mask:0xf
	v_fmac_f32_dpp v60, v14, v29 row_shl:14 row_mask:0xf bank_mask:0xf
	v_fmac_f32_dpp v60, v61, v25 row_shr:1 row_mask:0xf bank_mask:0xf
	v_fmac_f32_dpp v60, v14, v25 row_shl:15 row_mask:0xf bank_mask:0xf
	v_fmac_f32_e32 v60, v61, v37
	v_mov_b32_e32 v44, 0
	v_mov_b32_e32 v45, 0
	v_mov_b32_e32 v14, 0
	v_mov_b32_e32 v15, 0
	v_mov_b32_e32 v16, 0
	v_mov_b32_e32 v17, 0
	s_cbranch_vccnz .LBB0_1200
	ds_read_b128 v[42:45], v227 offset:2576
	ds_read_b128 v[14:17], v227 offset:3600
.LBB0_1200:
	v_pk_mul_f32 v[76:77], v[6:7], v[190:191]
	v_pk_mul_f32 v[72:73], v[10:11], v[192:193]
	v_pk_mul_f32 v[4:5], v[4:5], v[188:189] op_sel_hi:[1,0]
	v_pk_mul_f32 v[2:3], v[2:3], v[188:189]
	v_pk_mul_f32 v[74:75], v[8:9], v[190:191] op_sel_hi:[1,0]
	s_nop 1
	v_mov_b32_dpp v7, v2 row_ror:1 row_mask:0xf bank_mask:0xf
	v_mov_b32_dpp v6, v2 row_ror:2 row_mask:0xf bank_mask:0xf
	v_mov_b32_dpp v7, v50 row_shr:1 row_mask:0xf bank_mask:0xf
	v_mov_b32_dpp v6, v50 row_shr:2 row_mask:0xf bank_mask:0xf
	v_mov_b32_e32 v8, v50
	v_fma_f32 v10, v26, v6, v38
	v_mov_b32_e32 v9, v22
	v_mov_b32_e32 v6, v34
	v_pk_mul_f32 v[6:7], v[8:9], v[6:7]
	v_mov_b32_e32 v11, v23
	v_add_f32_e32 v7, v7, v10
	v_add_f32_e32 v7, v6, v7
	s_nop 1
	v_mov_b32_dpp v9, v3 row_ror:1 row_mask:0xf bank_mask:0xf
	v_mov_b32_dpp v6, v3 row_ror:2 row_mask:0xf bank_mask:0xf
	v_mov_b32_dpp v9, v51 row_shr:1 row_mask:0xf bank_mask:0xf
	v_mov_b32_dpp v6, v51 row_shr:2 row_mask:0xf bank_mask:0xf
	v_mov_b32_e32 v10, v51
	v_mov_b32_e32 v8, v35
	v_fma_f32 v6, v27, v6, v39
	v_pk_mul_f32 v[8:9], v[10:11], v[8:9]
	v_mov_b32_e32 v46, v192
	v_add_f32_e32 v6, v9, v6
	v_mov_b32_e32 v47, v192
	v_add_f32_e32 v6, v8, v6
	s_nop 1
	v_mov_b32_dpp v9, v4 row_ror:1 row_mask:0xf bank_mask:0xf
	v_mov_b32_dpp v8, v4 row_ror:2 row_mask:0xf bank_mask:0xf
	v_mov_b32_dpp v9, v52 row_shr:1 row_mask:0xf bank_mask:0xf
	v_mov_b32_dpp v8, v52 row_shr:2 row_mask:0xf bank_mask:0xf
	v_pk_mul_f32 v[64:65], v[12:13], v[46:47]
	v_fma_f32 v12, v28, v8, v40
	v_mov_b32_e32 v10, v52
	v_mov_b32_e32 v11, v24
	v_mov_b32_e32 v8, v36
	v_pk_mul_f32 v[8:9], v[10:11], v[8:9]
	v_mov_b32_e32 v13, v25
	v_add_f32_e32 v9, v9, v12
	v_add_f32_e32 v8, v8, v9
	s_nop 1
	v_mov_b32_dpp v11, v5 row_ror:1 row_mask:0xf bank_mask:0xf
	v_mov_b32_dpp v9, v5 row_ror:2 row_mask:0xf bank_mask:0xf
	v_mov_b32_dpp v11, v53 row_shr:1 row_mask:0xf bank_mask:0xf
	v_mov_b32_dpp v9, v53 row_shr:2 row_mask:0xf bank_mask:0xf
	v_mov_b32_e32 v12, v53
	v_mov_b32_e32 v10, v37
	v_fma_f32 v9, v29, v9, v41
	v_pk_mul_f32 v[10:11], v[12:13], v[10:11]
	v_mov_b32_e32 v12, v2
	v_add_f32_e32 v9, v11, v9
	v_add_f32_e32 v9, v10, v9
	s_nop 1
	v_mov_b32_dpp v11, v76 row_ror:1 row_mask:0xf bank_mask:0xf
	v_mov_b32_dpp v10, v76 row_ror:2 row_mask:0xf bank_mask:0xf
	v_mov_b32_dpp v11, v2 row_shr:1 row_mask:0xf bank_mask:0xf
	v_mov_b32_dpp v10, v2 row_shr:2 row_mask:0xf bank_mask:0xf
	v_mov_b32_e32 v13, v22
	v_fma_f32 v46, v26, v10, v38
	v_mov_b32_e32 v10, v34
	v_pk_mul_f32 v[10:11], v[12:13], v[10:11]
	v_mov_b32_e32 v12, v35
	v_add_f32_e32 v2, v11, v46
	v_add_f32_e32 v11, v10, v2
	s_nop 1
	v_mov_b32_dpp v13, v77 row_ror:1 row_mask:0xf bank_mask:0xf
	v_mov_b32_dpp v2, v77 row_ror:2 row_mask:0xf bank_mask:0xf
	v_mov_b32_dpp v13, v3 row_shr:1 row_mask:0xf bank_mask:0xf
	v_mov_b32_dpp v2, v3 row_shr:2 row_mask:0xf bank_mask:0xf
	s_waitcnt lgkmcnt(0)
; __device__ __forceinline__ unsigned cvt_pk_bf16(float lo, float hi) { unsigned r; asm volatile("v_cvt_pk_bf16_f32 %0, %1, %2" : "=v"(r) : "v"(lo), "v"(hi)); return r; }
;     __device__ __forceinline__ void operator()(f32x4 (&acc)[2][2][4][2], const Unit& u, int ui, int wr, int wc, int fr_, int fq_) const {
;     ...
;                     for (int m = 3; m >= 0; --m) { f32x4 cur = acc[ai][bj][m][n], res;
; #pragma unroll
;                         for (int j = 0; j < 4; ++j) { const float c = cur[j]; const float pv = (m > 0) ? acc[ai][bj][m > 0 ? m - 1 : 0][n][j] : (fr == 15 ? c63[j] : c62[j]); float t1, t2;
;                             asm volatile("s_nop 1\n\tv_mov_b32_dpp %0, %3 row_ror:1 row_mask:0xf bank_mask:0xf\n\tv_mov_b32_dpp %1, %3 row_ror:2 row_mask:0xf bank_mask:0xf\n\t"
;                                          "v_mov_b32_dpp %0, %2 row_shr:1 row_mask:0xf bank_mask:0xf\n\tv_mov_b32_dpp %1, %2 row_shr:2 row_mask:0xf bank_mask:0xf"
;                                          : "=&v"(t1), "=&v"(t2) : "v"(c), "v"(pv));
;                             res[j] = bb[j] + w0[j] * t2 + w1[j] * t1 + w2[j] * c; }
;                         asm volatile("" : "+v"(res[0]), "+v"(res[1]), "+v"(res[2]), "+v"(res[3]));
;                         acc[ai][bj][m][n] = res; } }
;                 asm volatile("" ::: "memory"); }
;         const int row0 = u.pm * BM + wr * 64 + fr;
; #pragma unroll
;         for (int ai = 0; ai < 2; ++ai)
; #pragma unroll
;             for (int m = 0; m < 4; ++m) { float gv[8];
; #pragma unroll
;                 for (int n = 0; n < 2; ++n)
; #pragma unroll
;                     for (int j = 0; j < 4; ++j) { const float g = acc[ai][0][m][n][j], up = acc[ai][1][m][n][j]; gv[n * 4 + j] = g * __builtin_amdgcn_rcpf(1.0f + __builtin_amdgcn_exp2f(g * -1.4426950408889634f)) * up; }
;                 u32x4 w; w.x = cvt_pk_bf16(gv[0], gv[1]); w.y = cvt_pk_bf16(gv[2], gv[3]); w.z = cvt_pk_bf16(gv[4], gv[5]); w.w = cvt_pk_bf16(gv[6], gv[7]);
;                 *(u32x4*)(G + (size_t)(row0 + ai * HALF + m * 16) * 2816 + fbase) = w; asm volatile("" ::: "memory"); }
	v_cndmask_b32_e64 v17, v45, v17, s[8:9]
	v_fma_f32 v10, v27, v2, v39
	v_mov_b32_e32 v2, v3
	v_mov_b32_e32 v3, v23
	v_pk_mul_f32 v[2:3], v[2:3], v[12:13]
	v_mov_b32_e32 v12, v4
	v_add_f32_e32 v3, v3, v10
	v_add_f32_e32 v10, v2, v3
	s_nop 1
	v_mov_b32_dpp v3, v74 row_ror:1 row_mask:0xf bank_mask:0xf
	v_mov_b32_dpp v2, v74 row_ror:2 row_mask:0xf bank_mask:0xf
	v_mov_b32_dpp v3, v4 row_shr:1 row_mask:0xf bank_mask:0xf
	v_mov_b32_dpp v2, v4 row_shr:2 row_mask:0xf bank_mask:0xf
	v_mov_b32_e32 v13, v24
	v_fma_f32 v46, v28, v2, v40
	v_mov_b32_e32 v2, v36
	v_pk_mul_f32 v[2:3], v[12:13], v[2:3]
	v_mov_b32_e32 v4, v5
	v_add_f32_e32 v3, v3, v46
	v_add_f32_e32 v12, v2, v3
	s_nop 1
	v_mov_b32_dpp v3, v75 row_ror:1 row_mask:0xf bank_mask:0xf
	v_mov_b32_dpp v2, v75 row_ror:2 row_mask:0xf bank_mask:0xf
	v_mov_b32_dpp v3, v5 row_shr:1 row_mask:0xf bank_mask:0xf
	v_mov_b32_dpp v2, v5 row_shr:2 row_mask:0xf bank_mask:0xf
	v_mov_b32_e32 v5, v25
	v_fma_f32 v13, v29, v2, v41
	v_mov_b32_e32 v2, v37
	v_pk_mul_f32 v[2:3], v[4:5], v[2:3]
	v_mov_b32_e32 v4, v76
	v_add_f32_e32 v3, v3, v13
	v_add_f32_e32 v13, v2, v3
	s_nop 1
	v_mov_b32_dpp v3, v72 row_ror:1 row_mask:0xf bank_mask:0xf
	v_mov_b32_dpp v2, v72 row_ror:2 row_mask:0xf bank_mask:0xf
	v_mov_b32_dpp v3, v76 row_shr:1 row_mask:0xf bank_mask:0xf
	v_mov_b32_dpp v2, v76 row_shr:2 row_mask:0xf bank_mask:0xf
	v_mov_b32_e32 v5, v22
	v_fma_f32 v46, v26, v2, v38
	v_mov_b32_e32 v2, v34
	v_pk_mul_f32 v[2:3], v[4:5], v[2:3]
	v_mov_b32_e32 v4, v77
	v_add_f32_e32 v3, v3, v46
	v_add_f32_e32 v47, v2, v3
	s_nop 1
	v_mov_b32_dpp v3, v73 row_ror:1 row_mask:0xf bank_mask:0xf
	v_mov_b32_dpp v2, v73 row_ror:2 row_mask:0xf bank_mask:0xf
	v_mov_b32_dpp v3, v77 row_shr:1 row_mask:0xf bank_mask:0xf
	v_mov_b32_dpp v2, v77 row_shr:2 row_mask:0xf bank_mask:0xf
	v_mov_b32_e32 v5, v23
	v_fma_f32 v46, v27, v2, v39
	v_mov_b32_e32 v2, v35
	v_pk_mul_f32 v[2:3], v[4:5], v[2:3]
	v_mov_b32_e32 v4, v74
	v_add_f32_e32 v3, v3, v46
	v_add_f32_e32 v46, v2, v3
	s_nop 1
	v_mov_b32_dpp v3, v64 row_ror:1 row_mask:0xf bank_mask:0xf
	v_mov_b32_dpp v2, v64 row_ror:2 row_mask:0xf bank_mask:0xf
	v_mov_b32_dpp v3, v74 row_shr:1 row_mask:0xf bank_mask:0xf
	v_mov_b32_dpp v2, v74 row_shr:2 row_mask:0xf bank_mask:0xf
	v_mov_b32_e32 v5, v24
	v_fma_f32 v50, v28, v2, v40
	v_mov_b32_e32 v2, v36
	v_pk_mul_f32 v[2:3], v[4:5], v[2:3]
	v_mov_b32_e32 v4, v75
	v_add_f32_e32 v3, v3, v50
	v_add_f32_e32 v50, v2, v3
	s_nop 1
	v_mov_b32_dpp v3, v65 row_ror:1 row_mask:0xf bank_mask:0xf
	v_mov_b32_dpp v2, v65 row_ror:2 row_mask:0xf bank_mask:0xf
	v_mov_b32_dpp v3, v75 row_shr:1 row_mask:0xf bank_mask:0xf
	v_mov_b32_dpp v2, v75 row_shr:2 row_mask:0xf bank_mask:0xf
	v_mov_b32_e32 v5, v25
	v_fma_f32 v51, v29, v2, v41
	v_mov_b32_e32 v2, v37
	v_pk_mul_f32 v[2:3], v[4:5], v[2:3]
	v_cndmask_b32_e64 v4, v43, v15, s[8:9]
	v_add_f32_e32 v3, v3, v51
	v_add_f32_e32 v51, v2, v3
	v_cndmask_b32_e64 v3, v42, v14, s[8:9]
	v_cndmask_b32_e64 v2, v44, v16, s[8:9]
	s_nop 1
	v_mov_b32_dpp v16, v3 row_ror:1 row_mask:0xf bank_mask:0xf
	v_mov_b32_dpp v42, v3 row_ror:2 row_mask:0xf bank_mask:0xf
	v_mov_b32_dpp v16, v72 row_shr:1 row_mask:0xf bank_mask:0xf
	v_mov_b32_dpp v42, v72 row_shr:2 row_mask:0xf bank_mask:0xf
	s_nop 1
	v_mov_b32_dpp v3, v4 row_ror:1 row_mask:0xf bank_mask:0xf
	v_mov_b32_dpp v43, v4 row_ror:2 row_mask:0xf bank_mask:0xf
	v_mov_b32_dpp v3, v73 row_shr:1 row_mask:0xf bank_mask:0xf
	v_mov_b32_dpp v43, v73 row_shr:2 row_mask:0xf bank_mask:0xf
	s_nop 1
	v_mov_b32_dpp v5, v2 row_ror:1 row_mask:0xf bank_mask:0xf
	v_mov_b32_dpp v44, v2 row_ror:2 row_mask:0xf bank_mask:0xf
	v_mov_b32_dpp v5, v64 row_shr:1 row_mask:0xf bank_mask:0xf
	v_mov_b32_dpp v44, v64 row_shr:2 row_mask:0xf bank_mask:0xf
	v_mov_b32_e32 v14, v64
	v_mov_b32_e32 v15, v24
	v_mov_b32_e32 v4, v36
	v_pk_mul_f32 v[4:5], v[14:15], v[4:5]
	v_fma_f32 v2, v28, v44, v40
	v_add_f32_e32 v2, v5, v2
	v_add_f32_e32 v15, v4, v2
	v_mov_b32_e32 v4, v73
	v_mov_b32_e32 v5, v23
	v_mov_b32_e32 v2, v35
	v_pk_mul_f32 v[2:3], v[4:5], v[2:3]
	v_fma_f32 v4, v27, v43, v39
	v_add_f32_e32 v3, v3, v4
	v_mov_b32_e32 v73, v22
	v_mov_b32_e32 v35, v16
	v_add_f32_e32 v27, v2, v3
	v_pk_mul_f32 v[2:3], v[72:73], v[34:35]
	v_fma_f32 v4, v26, v42, v38
	v_add_f32_e32 v3, v3, v4
	v_add_f32_e32 v26, v2, v3
	s_nop 1
	v_mov_b32_dpp v3, v17 row_ror:1 row_mask:0xf bank_mask:0xf
	v_mov_b32_dpp v2, v17 row_ror:2 row_mask:0xf bank_mask:0xf
	v_mov_b32_dpp v3, v65 row_shr:1 row_mask:0xf bank_mask:0xf
	v_mov_b32_dpp v2, v65 row_shr:2 row_mask:0xf bank_mask:0xf
	v_mov_b32_e32 v24, v65
	v_fmac_f32_e32 v41, v29, v2
	v_mov_b32_e32 v2, v37
	v_pk_mul_f32 v[2:3], v[24:25], v[2:3]
	v_mul_f32_e32 v22, s98, v123
	v_add_f32_e32 v3, v3, v41
	v_add_f32_e32 v28, v2, v3
	v_mul_f32_e32 v2, s98, v223
	v_mul_f32_e32 v3, s98, v224
	v_exp_f32_e32 v2, v2
	v_exp_f32_e32 v3, v3
	v_mul_f32_e32 v4, s98, v221
	v_mul_f32_e32 v5, s98, v222
	v_mul_f32_e32 v16, s98, v126
	v_mul_f32_e32 v17, s98, v122
	v_exp_f32_e32 v22, v22
	v_mul_f32_e32 v23, s98, v124
	v_exp_f32_e32 v4, v4
	v_exp_f32_e32 v5, v5
	v_exp_f32_e32 v16, v16
	v_exp_f32_e32 v17, v17
	v_exp_f32_e32 v23, v23
	v_add_f32_e32 v2, 1.0, v2
	v_add_f32_e32 v3, 1.0, v3
	v_add_f32_e32 v22, 1.0, v22
	v_rcp_f32_e32 v2, v2
	v_rcp_f32_e32 v3, v3
	v_add_f32_e32 v4, 1.0, v4
	v_add_f32_e32 v5, 1.0, v5
	v_add_f32_e32 v16, 1.0, v16
	v_add_f32_e32 v17, 1.0, v17
	v_rcp_f32_e32 v22, v22
	v_add_f32_e32 v23, 1.0, v23
	v_rcp_f32_e32 v4, v4
	v_rcp_f32_e32 v5, v5
	v_rcp_f32_e32 v16, v16
	v_rcp_f32_e32 v17, v17
	v_rcp_f32_e32 v23, v23
	s_lshl_b32 s0, s76, 8
	v_mul_f32_e32 v2, v223, v2
	v_mul_f32_e32 v3, v224, v3
	v_mul_f32_e32 v22, v123, v22
	s_add_i32 s0, s0, s68
; __device__ __forceinline__ unsigned cvt_pk_bf16(float lo, float hi) { unsigned r; asm volatile("v_cvt_pk_bf16_f32 %0, %1, %2" : "=v"(r) : "v"(lo), "v"(hi)); return r; }
;     __device__ __forceinline__ void operator()(f32x4 (&acc)[2][2][4][2], const Unit& u, int ui, int wr, int wc, int fr_, int fq_) const {
;     ...
;         const int row0 = u.pm * BM + wr * 64 + fr;
; #pragma unroll
;         for (int ai = 0; ai < 2; ++ai)
; #pragma unroll
;             for (int m = 0; m < 4; ++m) { float gv[8];
; #pragma unroll
;                 for (int n = 0; n < 2; ++n)
; #pragma unroll
;                     for (int j = 0; j < 4; ++j) { const float g = acc[ai][0][m][n][j], up = acc[ai][1][m][n][j]; gv[n * 4 + j] = g * __builtin_amdgcn_rcpf(1.0f + __builtin_amdgcn_exp2f(g * -1.4426950408889634f)) * up; }
;                 u32x4 w; w.x = cvt_pk_bf16(gv[0], gv[1]); w.y = cvt_pk_bf16(gv[2], gv[3]); w.z = cvt_pk_bf16(gv[4], gv[5]); w.w = cvt_pk_bf16(gv[6], gv[7]);
;                 *(u32x4*)(G + (size_t)(row0 + ai * HALF + m * 16) * 2816 + fbase) = w; asm volatile("" ::: "memory"); }
	v_mul_f32_e32 v2, v2, v97
	v_mul_f32_e32 v3, v3, v96
	v_mul_f32_e32 v4, v221, v4
	v_mul_f32_e32 v5, v222, v5
	v_mul_f32_e32 v16, v126, v16
	v_mul_f32_e32 v17, v122, v17
	v_mul_f32_e32 v25, v22, v59
	v_mul_f32_e32 v22, v124, v23
	v_add_u32_e32 v14, s0, v210
	v_mul_f32_e32 v4, v4, v95
	v_mul_f32_e32 v5, v5, v94
	v_mul_f32_e32 v16, v16, v62
	v_mul_f32_e32 v17, v17, v58
	v_mul_f32_e32 v29, v22, v60
	v_cvt_pk_bf16_f32 v22, v2, v3
	v_mov_b64_e32 v[2:3], s[38:39]
	v_cvt_pk_bf16_f32 v23, v4, v5
	v_cvt_pk_bf16_f32 v24, v16, v17
	v_mad_i64_i32 v[16:17], s[0:1], v14, s83, v[2:3]
	v_lshlrev_b64 v[4:5], 1, v[186:187]
	v_lshl_add_u64 v[16:17], v[16:17], 0, v[4:5]
	v_cvt_pk_bf16_f32 v25, v25, v29
	global_store_dwordx4 v[16:17], v[22:25], off
	v_mul_f32_e32 v29, s98, v218
	v_exp_f32_e32 v29, v29
	v_mul_f32_e32 v22, s98, v217
	v_exp_f32_e32 v22, v22
	v_mul_f32_e32 v23, s98, v219
	v_exp_f32_e32 v23, v23
	v_mul_f32_e32 v24, s98, v225
	v_add_f32_e32 v22, 1.0, v22
	v_rcp_f32_e32 v22, v22
	v_add_f32_e32 v23, 1.0, v23
	v_rcp_f32_e32 v23, v23
	v_exp_f32_e32 v24, v24
	v_mul_f32_e32 v22, v217, v22
	v_mul_f32_e32 v25, v22, v108
	v_mul_f32_e32 v22, v219, v23
	v_add_f32_e32 v23, 1.0, v24
	v_mul_f32_e32 v34, s98, v220
	v_rcp_f32_e32 v23, v23
	v_mul_f32_e32 v24, s98, v144
	v_exp_f32_e32 v34, v34
	v_exp_f32_e32 v24, v24
	v_add_f32_e32 v16, 1.0, v29
	v_mul_f32_e32 v29, v22, v109
	v_mul_f32_e32 v22, v225, v23
	v_mul_f32_e32 v23, s98, v145
	v_add_f32_e32 v17, 1.0, v34
	v_mul_f32_e32 v34, v22, v69
	v_add_f32_e32 v22, 1.0, v24
	v_exp_f32_e32 v23, v23
	v_mul_f32_e32 v24, s98, v226
	v_exp_f32_e32 v24, v24
	v_rcp_f32_e32 v22, v22
	v_add_f32_e32 v23, 1.0, v23
	v_rcp_f32_e32 v16, v16
	v_rcp_f32_e32 v23, v23
	v_add_f32_e32 v24, 1.0, v24
	v_rcp_f32_e32 v17, v17
	v_rcp_f32_e32 v24, v24
	v_mul_f32_e32 v22, v144, v22
	v_mul_f32_e32 v16, v218, v16
	v_mul_f32_e32 v35, v22, v67
	v_mul_f32_e32 v22, v145, v23
	v_mul_f32_e32 v16, v16, v127
	v_mul_f32_e32 v17, v220, v17
	v_mul_f32_e32 v36, v22, v68
	v_mul_f32_e32 v22, v226, v24
	v_mul_f32_e32 v17, v17, v125
	v_mul_f32_e32 v37, v22, v70
	v_cvt_pk_bf16_f32 v22, v16, v17
	v_add_u32_e32 v16, 16, v14
	v_mad_i64_i32 v[16:17], s[0:1], v16, s83, v[2:3]
	v_lshl_add_u64 v[16:17], v[16:17], 0, v[4:5]
	v_cvt_pk_bf16_f32 v23, v25, v29
	v_cvt_pk_bf16_f32 v24, v34, v35
	v_cvt_pk_bf16_f32 v25, v36, v37
	global_store_dwordx4 v[16:17], v[22:25], off
	v_mul_f32_e32 v29, s98, v213
	v_exp_f32_e32 v29, v29
	v_mul_f32_e32 v22, s98, v154
	v_exp_f32_e32 v22, v22
	v_mul_f32_e32 v23, s98, v214
	v_exp_f32_e32 v23, v23
	v_mul_f32_e32 v24, s98, v142
	v_add_f32_e32 v22, 1.0, v22
	v_rcp_f32_e32 v22, v22
	v_add_f32_e32 v23, 1.0, v23
	v_rcp_f32_e32 v23, v23
	v_exp_f32_e32 v24, v24
	v_mul_f32_e32 v22, v154, v22
	v_mul_f32_e32 v25, v22, v100
	v_mul_f32_e32 v22, v214, v23
	v_add_f32_e32 v23, 1.0, v24
	v_mul_f32_e32 v34, s98, v216
	v_rcp_f32_e32 v23, v23
	v_mul_f32_e32 v24, s98, v136
	v_exp_f32_e32 v34, v34
	v_exp_f32_e32 v24, v24
	v_add_f32_e32 v16, 1.0, v29
	v_mul_f32_e32 v29, v22, v101
	v_mul_f32_e32 v22, v142, v23
	v_mul_f32_e32 v23, s98, v137
	v_add_f32_e32 v17, 1.0, v34
	v_mul_f32_e32 v34, v22, v56
	v_add_f32_e32 v22, 1.0, v24
	v_exp_f32_e32 v23, v23
	v_mul_f32_e32 v24, s98, v143
	v_exp_f32_e32 v24, v24
	v_rcp_f32_e32 v22, v22
	v_add_f32_e32 v23, 1.0, v23
	v_rcp_f32_e32 v16, v16
	v_rcp_f32_e32 v23, v23
	v_add_f32_e32 v24, 1.0, v24
	v_rcp_f32_e32 v17, v17
	v_rcp_f32_e32 v24, v24
	v_mul_f32_e32 v22, v136, v22
	v_mul_f32_e32 v16, v213, v16
	v_mul_f32_e32 v30, v22, v30
	v_mul_f32_e32 v22, v137, v23
	v_mul_f32_e32 v16, v16, v107
	v_mul_f32_e32 v17, v216, v17
	v_mul_f32_e32 v31, v22, v31
	v_mul_f32_e32 v22, v143, v24
	v_mul_f32_e32 v17, v17, v105
	v_mul_f32_e32 v35, v22, v66
	v_cvt_pk_bf16_f32 v22, v16, v17
	v_add_u32_e32 v16, 32, v14
	v_mad_i64_i32 v[16:17], s[0:1], v16, s83, v[2:3]
	v_cvt_pk_bf16_f32 v23, v25, v29
	v_cvt_pk_bf16_f32 v24, v34, v30
	v_lshl_add_u64 v[16:17], v[16:17], 0, v[4:5]
	v_cvt_pk_bf16_f32 v25, v31, v35
	global_store_dwordx4 v[16:17], v[22:25], off
	v_mul_f32_e32 v29, s98, v211
	v_exp_f32_e32 v29, v29
	v_mul_f32_e32 v24, s98, v133
	v_exp_f32_e32 v24, v24
	v_mul_f32_e32 v25, s98, v131
	v_exp_f32_e32 v25, v25
	v_mul_f32_e32 v30, s98, v212
	v_add_f32_e32 v24, 1.0, v24
	v_rcp_f32_e32 v24, v24
	v_exp_f32_e32 v30, v30
	v_add_f32_e32 v16, 1.0, v29
	v_mul_f32_e32 v22, s98, v152
	v_mul_f32_e32 v24, v133, v24
	v_mul_f32_e32 v20, v24, v20
	v_add_f32_e32 v24, 1.0, v25
	v_mul_f32_e32 v25, s98, v132
	v_mul_f32_e32 v23, s98, v153
	v_exp_f32_e32 v25, v25
	v_mul_f32_e32 v29, s98, v135
	v_exp_f32_e32 v22, v22
	v_exp_f32_e32 v23, v23
	v_exp_f32_e32 v29, v29
	v_add_f32_e32 v17, 1.0, v30
	v_rcp_f32_e32 v24, v24
	v_add_f32_e32 v25, 1.0, v25
	v_rcp_f32_e32 v16, v16
	v_rcp_f32_e32 v17, v17
	v_add_f32_e32 v22, 1.0, v22
	v_add_f32_e32 v23, 1.0, v23
	v_rcp_f32_e32 v25, v25
	v_add_f32_e32 v29, 1.0, v29
	v_rcp_f32_e32 v22, v22
	v_rcp_f32_e32 v23, v23
	v_rcp_f32_e32 v29, v29
	v_mul_f32_e32 v24, v131, v24
	v_mul_f32_e32 v16, v211, v16
	v_mul_f32_e32 v17, v212, v17
	v_mul_f32_e32 v18, v24, v18
	v_mul_f32_e32 v24, v132, v25
	v_mul_f32_e32 v16, v16, v104
	v_mul_f32_e32 v17, v17, v103
	v_mul_f32_e32 v22, v152, v22
	v_mul_f32_e32 v23, v153, v23
	v_mul_f32_e32 v19, v24, v19
	v_mul_f32_e32 v24, v135, v29
	v_mul_f32_e32 v22, v22, v98
	v_mul_f32_e32 v23, v23, v99
	v_mul_f32_e32 v21, v24, v21
	v_cvt_pk_bf16_f32 v16, v16, v17
	v_cvt_pk_bf16_f32 v17, v22, v23
	v_cvt_pk_bf16_f32 v18, v20, v18
	v_add_u32_e32 v20, 48, v14
	v_cvt_pk_bf16_f32 v19, v19, v21
	v_mad_i64_i32 v[20:21], s[0:1], v20, s83, v[2:3]
	v_lshl_add_u64 v[20:21], v[20:21], 0, v[4:5]
	global_store_dwordx4 v[20:21], v[16:19], off
; __device__ __forceinline__ unsigned cvt_pk_bf16(float lo, float hi) { unsigned r; asm volatile("v_cvt_pk_bf16_f32 %0, %1, %2" : "=v"(r) : "v"(lo), "v"(hi)); return r; }
;     __device__ __forceinline__ void operator()(f32x4 (&acc)[2][2][4][2], const Unit& u, int ui, int wr, int wc, int fr_, int fq_) const {
;     ...
;         const int row0 = u.pm * BM + wr * 64 + fr;
; #pragma unroll
;         for (int ai = 0; ai < 2; ++ai)
; #pragma unroll
;             for (int m = 0; m < 4; ++m) { float gv[8];
; #pragma unroll
;                 for (int n = 0; n < 2; ++n)
; #pragma unroll
;                     for (int j = 0; j < 4; ++j) { const float g = acc[ai][0][m][n][j], up = acc[ai][1][m][n][j]; gv[n * 4 + j] = g * __builtin_amdgcn_rcpf(1.0f + __builtin_amdgcn_exp2f(g * -1.4426950408889634f)) * up; }
;                 u32x4 w; w.x = cvt_pk_bf16(gv[0], gv[1]); w.y = cvt_pk_bf16(gv[2], gv[3]); w.z = cvt_pk_bf16(gv[4], gv[5]); w.w = cvt_pk_bf16(gv[6], gv[7]);
;                 *(u32x4*)(G + (size_t)(row0 + ai * HALF + m * 16) * 2816 + fbase) = w; asm volatile("" ::: "memory"); }
	v_mul_f32_e32 v22, s98, v102
	v_mul_f32_e32 v21, s98, v106
	v_mul_f32_e32 v16, s98, v134
	v_mul_f32_e32 v17, s98, v130
	v_mul_f32_e32 v18, s98, v32
	v_exp_f32_e32 v16, v16
	v_exp_f32_e32 v17, v17
	v_exp_f32_e32 v18, v18
	v_mul_f32_e32 v19, s98, v33
	v_exp_f32_e32 v22, v22
	v_exp_f32_e32 v19, v19
	v_exp_f32_e32 v21, v21
	v_mul_f32_e32 v23, s98, v48
	v_exp_f32_e32 v23, v23
	v_mul_f32_e32 v24, s98, v49
	v_add_f32_e32 v16, 1.0, v16
	v_add_f32_e32 v17, 1.0, v17
	v_add_f32_e32 v18, 1.0, v18
	v_add_f32_e32 v22, 1.0, v22
	v_exp_f32_e32 v24, v24
	v_rcp_f32_e32 v16, v16
	v_rcp_f32_e32 v17, v17
	v_rcp_f32_e32 v18, v18
	v_add_f32_e32 v19, 1.0, v19
	v_add_f32_e32 v21, 1.0, v21
	v_rcp_f32_e32 v22, v22
	v_rcp_f32_e32 v19, v19
	v_rcp_f32_e32 v21, v21
	v_add_f32_e32 v23, 1.0, v23
	v_rcp_f32_e32 v23, v23
	v_add_f32_e32 v24, 1.0, v24
	v_mul_f32_e32 v16, v134, v16
	v_mul_f32_e32 v17, v130, v17
	v_mul_f32_e32 v18, v32, v18
	v_mul_f32_e32 v22, v102, v22
	v_rcp_f32_e32 v24, v24
	v_mul_f32_e32 v16, v16, v78
	v_mul_f32_e32 v17, v17, v55
	v_mul_f32_e32 v18, v18, v54
	v_mul_f32_e32 v19, v33, v19
	v_mul_f32_e32 v21, v106, v21
	v_mul_f32_e32 v22, v22, v27
	v_mul_f32_e32 v19, v19, v57
	v_mul_f32_e32 v21, v21, v26
	v_cvt_pk_bf16_f32 v16, v16, v17
	v_cvt_pk_bf16_f32 v17, v18, v19
	v_cvt_pk_bf16_f32 v18, v21, v22
	v_mul_f32_e32 v22, s98, v215
	v_add_u32_e32 v20, 0x80, v14
	v_mul_f32_e32 v23, v48, v23
	v_exp_f32_e32 v22, v22
	v_mul_f32_e32 v15, v23, v15
	v_mul_f32_e32 v23, v49, v24
	v_mad_i64_i32 v[20:21], s[0:1], v20, s83, v[2:3]
	v_mul_f32_e32 v23, v23, v28
	v_cvt_pk_bf16_f32 v19, v15, v23
	v_lshl_add_u64 v[20:21], v[20:21], 0, v[4:5]
	v_mul_f32_e32 v15, s98, v151
	v_exp_f32_e32 v15, v15
	global_store_dwordx4 v[20:21], v[16:19], off
	v_mul_f32_e32 v20, s98, v118
	v_mul_f32_e32 v21, s98, v119
	v_mul_f32_e32 v17, s98, v150
	v_mul_f32_e32 v18, s98, v155
	v_mul_f32_e32 v19, s98, v120
	v_add_f32_e32 v16, 1.0, v22
	v_exp_f32_e32 v17, v17
	v_exp_f32_e32 v18, v18
	v_exp_f32_e32 v19, v19
	v_exp_f32_e32 v20, v20
	v_exp_f32_e32 v21, v21
	v_mul_f32_e32 v22, s98, v121
	v_exp_f32_e32 v22, v22
	v_add_f32_e32 v15, 1.0, v15
	v_rcp_f32_e32 v15, v15
	v_rcp_f32_e32 v16, v16
	v_add_f32_e32 v17, 1.0, v17
	v_add_f32_e32 v18, 1.0, v18
	v_add_f32_e32 v19, 1.0, v19
	v_add_f32_e32 v20, 1.0, v20
	v_add_f32_e32 v21, 1.0, v21
	v_rcp_f32_e32 v17, v17
	v_rcp_f32_e32 v18, v18
	v_rcp_f32_e32 v19, v19
	v_rcp_f32_e32 v20, v20
	v_rcp_f32_e32 v21, v21
	v_add_f32_e32 v22, 1.0, v22
	v_rcp_f32_e32 v22, v22
	v_mul_f32_e32 v15, v151, v15
	v_mul_f32_e32 v16, v215, v16
	v_mul_f32_e32 v15, v15, v93
	v_mul_f32_e32 v16, v16, v92
	v_mul_f32_e32 v17, v150, v17
	v_mul_f32_e32 v18, v155, v18
	v_mul_f32_e32 v19, v120, v19
	v_mul_f32_e32 v20, v118, v20
	v_mul_f32_e32 v21, v119, v21
	v_mul_f32_e32 v17, v17, v90
	v_mul_f32_e32 v18, v18, v91
	v_mul_f32_e32 v19, v19, v47
	v_mul_f32_e32 v20, v20, v46
	v_mul_f32_e32 v21, v21, v50
	v_mul_f32_e32 v22, v121, v22
	v_cvt_pk_bf16_f32 v16, v15, v16
	v_add_u32_e32 v15, 0x90, v14
	v_mul_f32_e32 v22, v22, v51
	v_cvt_pk_bf16_f32 v17, v17, v18
	v_cvt_pk_bf16_f32 v18, v19, v20
	v_cvt_pk_bf16_f32 v19, v21, v22
	v_mad_i64_i32 v[20:21], s[0:1], v15, s83, v[2:3]
	v_lshl_add_u64 v[20:21], v[20:21], 0, v[4:5]
	global_store_dwordx4 v[20:21], v[16:19], off
	v_mul_f32_e32 v20, s98, v114
	v_exp_f32_e32 v20, v20
	v_mul_f32_e32 v19, s98, v116
	v_exp_f32_e32 v19, v19
	v_mul_f32_e32 v15, s98, v147
	v_exp_f32_e32 v15, v15
	v_mul_f32_e32 v22, s98, v149
	v_add_f32_e32 v19, 1.0, v19
	v_rcp_f32_e32 v19, v19
	v_mul_f32_e32 v17, s98, v146
	v_mul_f32_e32 v21, s98, v117
	v_exp_f32_e32 v22, v22
	v_mul_f32_e32 v19, v116, v19
	v_mul_f32_e32 v19, v19, v11
	v_add_f32_e32 v11, 1.0, v20
	v_mul_f32_e32 v20, s98, v115
	v_exp_f32_e32 v20, v20
	v_exp_f32_e32 v17, v17
	v_mul_f32_e32 v18, s98, v148
	v_exp_f32_e32 v21, v21
	v_exp_f32_e32 v18, v18
	v_add_f32_e32 v15, 1.0, v15
	v_rcp_f32_e32 v11, v11
	v_add_f32_e32 v20, 1.0, v20
	v_rcp_f32_e32 v15, v15
	v_add_f32_e32 v16, 1.0, v22
	v_add_f32_e32 v17, 1.0, v17
	v_rcp_f32_e32 v20, v20
	v_add_f32_e32 v21, 1.0, v21
	v_rcp_f32_e32 v16, v16
	v_rcp_f32_e32 v17, v17
	v_add_f32_e32 v18, 1.0, v18
	v_rcp_f32_e32 v21, v21
	v_rcp_f32_e32 v18, v18
	v_mul_f32_e32 v11, v114, v11
	v_mul_f32_e32 v15, v147, v15
	v_mul_f32_e32 v22, v11, v10
	v_mul_f32_e32 v10, v115, v20
	v_mul_f32_e32 v15, v15, v89
	v_mul_f32_e32 v16, v149, v16
	v_mul_f32_e32 v17, v146, v17
	v_mul_f32_e32 v20, v10, v12
	v_mul_f32_e32 v10, v117, v21
	v_mul_f32_e32 v16, v16, v88
	v_mul_f32_e32 v17, v17, v84
	v_mul_f32_e32 v18, v148, v18
	v_mul_f32_e32 v13, v10, v13
	v_cvt_pk_bf16_f32 v10, v15, v16
	v_add_u32_e32 v15, 0xa0, v14
	v_mul_f32_e32 v18, v18, v85
	v_cvt_pk_bf16_f32 v11, v17, v18
	v_mad_i64_i32 v[16:17], s[0:1], v15, s83, v[2:3]
	v_mul_f32_e32 v15, s98, v139
	v_exp_f32_e32 v15, v15
	v_lshl_add_u64 v[16:17], v[16:17], 0, v[4:5]
	v_cvt_pk_bf16_f32 v12, v19, v22
	v_cvt_pk_bf16_f32 v13, v20, v13
	global_store_dwordx4 v[16:17], v[10:13], off
	v_mul_f32_e32 v16, s98, v110
	v_exp_f32_e32 v16, v16
	v_add_f32_e32 v10, 1.0, v15
	v_mul_f32_e32 v15, s98, v112
	v_exp_f32_e32 v15, v15
	v_mul_f32_e32 v18, s98, v141
	v_mul_f32_e32 v17, s98, v113
	v_exp_f32_e32 v18, v18
	v_add_f32_e32 v15, 1.0, v15
	v_rcp_f32_e32 v15, v15
	v_exp_f32_e32 v17, v17
	v_mul_f32_e32 v12, s98, v138
	v_mul_f32_e32 v13, s98, v140
	v_mul_f32_e32 v15, v112, v15
	v_mul_f32_e32 v15, v15, v7
	v_add_f32_e32 v7, 1.0, v16
	v_mul_f32_e32 v16, s98, v111
	v_exp_f32_e32 v16, v16
	v_exp_f32_e32 v12, v12
	v_exp_f32_e32 v13, v13
	v_rcp_f32_e32 v7, v7
	v_add_f32_e32 v16, 1.0, v16
	v_rcp_f32_e32 v10, v10
	v_add_f32_e32 v11, 1.0, v18
	v_rcp_f32_e32 v16, v16
	v_add_f32_e32 v17, 1.0, v17
	v_rcp_f32_e32 v11, v11
	v_rcp_f32_e32 v17, v17
	v_add_f32_e32 v12, 1.0, v12
	v_add_f32_e32 v13, 1.0, v13
	v_mul_f32_e32 v7, v110, v7
	v_mul_f32_e32 v10, v139, v10
	v_rcp_f32_e32 v12, v12
	v_rcp_f32_e32 v13, v13
	v_mul_f32_e32 v18, v7, v6
	v_mul_f32_e32 v6, v111, v16
	v_mul_f32_e32 v10, v10, v87
	v_mul_f32_e32 v11, v141, v11
	v_mul_f32_e32 v16, v6, v8
	v_mul_f32_e32 v6, v113, v17
	v_mul_f32_e32 v11, v11, v86
	v_mul_f32_e32 v9, v6, v9
	v_cvt_pk_bf16_f32 v6, v10, v11
	v_add_u32_e32 v10, 0xb0, v14
	v_mad_i64_i32 v[2:3], s[0:1], v10, s83, v[2:3]
	v_mul_f32_e32 v12, v138, v12
	v_mul_f32_e32 v13, v140, v13
	v_lshl_add_u64 v[2:3], v[2:3], 0, v[4:5]
	v_mul_f32_e32 v12, v12, v82
	v_mul_f32_e32 v13, v13, v83
	v_cvt_pk_bf16_f32 v7, v12, v13
	v_cvt_pk_bf16_f32 v8, v15, v18
	v_cvt_pk_bf16_f32 v9, v16, v9
	global_store_dwordx4 v[2:3], v[6:9], off
	s_andn2_b64 vcc, exec, s[6:7]
	s_mov_b64 s[0:1], -1
	s_cbranch_vccnz .LBB0_1171
	s_andn2_b64 vcc, exec, s[16:17]
	s_cbranch_vccnz .LBB0_1170
	s_barrier
	s_branch .LBB0_1170
